# best + nt hint on the single-use LayerNorm input streams (sub-block output, residual lo plane, f32 x)
# baseline (speedup 1.0000x reference)
; __device__ __forceinline__ void ln_panel(int pm, const float* resf, const bf16* rlo, const bf16* dlt, float* xo, const float* gam, const float* bet, bf16* xb, bf16* wlo, bool fin, float alpha) {
;     ...
;     for (int r = wave * 32; r < wave * 32 + 32; ++r) {
;         const size_t grow = (size_t)(pm * 256 + r) * DM + 4 * lane, prow = (size_t)r * DM + 4 * lane;
;         f32x4 v[4]; float s = 0.f;
; #pragma unroll
;         for (int j = 0; j < 4; ++j) { f32x4 x; const u32x2 d = *(const u32x2*)(dlt + prow + 256 * j);
;             if (resf) x = *(const f32x4*)(resf + grow + 256 * j);
;             else { const u32x2 h = *(const u32x2*)(xb + grow + 256 * j), l = *(const u32x2*)(rlo + prow + 256 * j);
.Lmy_ln1h_start:
	s_mov_b32 s98, 0
	s_add_i32 s0, s98, 0
	s_min_u32 s0, s0, 31
	s_lshl_b32 s0, s0, 11
	s_mov_b32 s1, 0
	v_lshl_add_u64 v[184:185], s[0:1], 0, v[178:179]
	v_lshl_add_u64 v[186:187], s[0:1], 0, v[172:173]
	v_lshl_add_u64 v[188:189], s[0:1], 0, v[176:177]
	global_load_dwordx2 v[82:83], v[184:185], off offset:-1024 nt
	global_load_dwordx2 v[84:85], v[184:185], off offset:-512 nt
	global_load_dwordx2 v[86:87], v[184:185], off offset:0 nt
	global_load_dwordx2 v[88:89], v[184:185], off offset:512 nt
	global_load_dwordx2 v[66:67], v[186:187], off offset:0
	global_load_dwordx2 v[68:69], v[186:187], off offset:512
	global_load_dwordx2 v[70:71], v[186:187], off offset:1024
	global_load_dwordx2 v[72:73], v[186:187], off offset:1536
	global_load_dwordx2 v[74:75], v[188:189], off offset:0 nt
	global_load_dwordx2 v[76:77], v[188:189], off offset:512 nt
	global_load_dwordx2 v[78:79], v[188:189], off offset:1024 nt
	global_load_dwordx2 v[80:81], v[188:189], off offset:1536 nt
	s_add_i32 s0, s98, 1
	s_min_u32 s0, s0, 31
	s_lshl_b32 s0, s0, 11
	s_mov_b32 s1, 0
	v_lshl_add_u64 v[184:185], s[0:1], 0, v[178:179]
	v_lshl_add_u64 v[186:187], s[0:1], 0, v[172:173]
	v_lshl_add_u64 v[188:189], s[0:1], 0, v[176:177]
	global_load_dwordx2 v[106:107], v[184:185], off offset:-1024 nt
	global_load_dwordx2 v[108:109], v[184:185], off offset:-512 nt
	global_load_dwordx2 v[110:111], v[184:185], off offset:0 nt
	global_load_dwordx2 v[112:113], v[184:185], off offset:512 nt
	global_load_dwordx2 v[90:91], v[186:187], off offset:0
	global_load_dwordx2 v[92:93], v[186:187], off offset:512
	global_load_dwordx2 v[94:95], v[186:187], off offset:1024
	global_load_dwordx2 v[96:97], v[186:187], off offset:1536
	global_load_dwordx2 v[98:99], v[188:189], off offset:0 nt
	global_load_dwordx2 v[100:101], v[188:189], off offset:512 nt
	global_load_dwordx2 v[102:103], v[188:189], off offset:1024 nt
	global_load_dwordx2 v[104:105], v[188:189], off offset:1536 nt
	s_waitcnt vmcnt(12)
	s_branch .Lmy_ln1h_entry

; __device__ __forceinline__ float bflo(unsigned u) { return __uint_as_float(u << 16); }
; __device__ __forceinline__ float bfhi(unsigned u) { return __uint_as_float(u & 0xffff0000u); }
; __device__ __forceinline__ void ln_panel(int pm, const float* resf, const bf16* rlo, const bf16* dlt, float* xo, const float* gam, const float* bet, bf16* xb, bf16* wlo, bool fin, float alpha) {
;     ...
;         for (int j = 0; j < 4; ++j) { f32x4 x; const u32x2 d = *(const u32x2*)(dlt + prow + 256 * j);
;             if (resf) x = *(const f32x4*)(resf + grow + 256 * j);
;             else { const u32x2 h = *(const u32x2*)(xb + grow + 256 * j), l = *(const u32x2*)(rlo + prow + 256 * j);
;                    x = (f32x4){bflo(h.x) + bflo(l.x), bfhi(h.x) + bfhi(l.x), bflo(h.y) + bflo(l.y), bfhi(h.y) + bfhi(l.y)}; }
;             v[j] = (f32x4){x.x * alpha + bflo(d.x), x.y * alpha + bfhi(d.x), x.z * alpha + bflo(d.y), x.w * alpha + bfhi(d.y)}; s += (v[j].x + v[j].y) + (v[j].z + v[j].w); }
;         const float mean = wave_sum(s) * (1.f / DM); float s2 = 0.f;
; #pragma unroll
;         for (int j = 0; j < 4; ++j) { v[j] = v[j] - mean; s2 += (v[j].x * v[j].x + v[j].y * v[j].y) + (v[j].z * v[j].z + v[j].w * v[j].w); }
;         const float rstd = 1.f / sqrtf(wave_sum(s2) * (1.f / DM) + LN_EPS);
.Lmy_ln1h_entry:
	v_lshlrev_b32_e32 v150, 16, v66
	v_and_b32_e32 v151, 0xffff0000, v66
	v_lshlrev_b32_e32 v152, 16, v74
	v_and_b32_e32 v153, 0xffff0000, v74
	v_pk_add_f32 v[150:151], v[150:151], v[152:153]
	v_lshlrev_b32_e32 v152, 16, v82
	v_and_b32_e32 v153, 0xffff0000, v82
	v_pk_fma_f32 v[114:115], v[150:151], v[164:165], v[152:153]
	v_lshlrev_b32_e32 v150, 16, v67
	v_and_b32_e32 v151, 0xffff0000, v67
	v_lshlrev_b32_e32 v152, 16, v75
	v_and_b32_e32 v153, 0xffff0000, v75
	v_pk_add_f32 v[150:151], v[150:151], v[152:153]
	v_lshlrev_b32_e32 v152, 16, v83
	v_and_b32_e32 v153, 0xffff0000, v83
	v_pk_fma_f32 v[116:117], v[150:151], v[164:165], v[152:153]
	v_lshlrev_b32_e32 v150, 16, v68
	v_and_b32_e32 v151, 0xffff0000, v68
	v_lshlrev_b32_e32 v152, 16, v76
	v_and_b32_e32 v153, 0xffff0000, v76
	v_pk_add_f32 v[150:151], v[150:151], v[152:153]
	v_lshlrev_b32_e32 v152, 16, v84
	v_and_b32_e32 v153, 0xffff0000, v84
	v_pk_fma_f32 v[118:119], v[150:151], v[164:165], v[152:153]
	v_lshlrev_b32_e32 v150, 16, v69
	v_and_b32_e32 v151, 0xffff0000, v69
	v_lshlrev_b32_e32 v152, 16, v77
	v_and_b32_e32 v153, 0xffff0000, v77
	v_pk_add_f32 v[150:151], v[150:151], v[152:153]
	v_lshlrev_b32_e32 v152, 16, v85
	v_and_b32_e32 v153, 0xffff0000, v85
	v_pk_fma_f32 v[120:121], v[150:151], v[164:165], v[152:153]
	v_lshlrev_b32_e32 v150, 16, v70
	v_and_b32_e32 v151, 0xffff0000, v70
	v_lshlrev_b32_e32 v152, 16, v78
	v_and_b32_e32 v153, 0xffff0000, v78
	v_pk_add_f32 v[150:151], v[150:151], v[152:153]
	v_lshlrev_b32_e32 v152, 16, v86
	v_and_b32_e32 v153, 0xffff0000, v86
	v_pk_fma_f32 v[122:123], v[150:151], v[164:165], v[152:153]
	v_lshlrev_b32_e32 v150, 16, v71
	v_and_b32_e32 v151, 0xffff0000, v71
	v_lshlrev_b32_e32 v152, 16, v79
	v_and_b32_e32 v153, 0xffff0000, v79
	v_pk_add_f32 v[150:151], v[150:151], v[152:153]
	v_lshlrev_b32_e32 v152, 16, v87
	v_and_b32_e32 v153, 0xffff0000, v87
	v_pk_fma_f32 v[124:125], v[150:151], v[164:165], v[152:153]
	v_lshlrev_b32_e32 v150, 16, v72
	v_and_b32_e32 v151, 0xffff0000, v72
	v_lshlrev_b32_e32 v152, 16, v80
	v_and_b32_e32 v153, 0xffff0000, v80
	v_pk_add_f32 v[150:151], v[150:151], v[152:153]
	v_lshlrev_b32_e32 v152, 16, v88
	v_and_b32_e32 v153, 0xffff0000, v88
	v_pk_fma_f32 v[126:127], v[150:151], v[164:165], v[152:153]
	v_lshlrev_b32_e32 v150, 16, v73
	v_and_b32_e32 v151, 0xffff0000, v73
	v_lshlrev_b32_e32 v152, 16, v81
	v_and_b32_e32 v153, 0xffff0000, v81
	v_pk_add_f32 v[150:151], v[150:151], v[152:153]
	v_lshlrev_b32_e32 v152, 16, v89
	v_and_b32_e32 v153, 0xffff0000, v89
	v_pk_fma_f32 v[128:129], v[150:151], v[164:165], v[152:153]
	v_pk_add_f32 v[154:155], v[114:115], v[116:117]
	v_pk_add_f32 v[156:157], v[118:119], v[120:121]
	v_pk_add_f32 v[154:155], v[154:155], v[156:157]
	v_pk_add_f32 v[156:157], v[122:123], v[124:125]
	v_pk_add_f32 v[154:155], v[154:155], v[156:157]
	v_pk_add_f32 v[156:157], v[126:127], v[128:129]
	v_pk_add_f32 v[154:155], v[154:155], v[156:157]
	v_add_f32_e32 v154, v154, v155
	s_nop 1
	v_add_f32_dpp v160, v154, v154 quad_perm:[1,0,3,2] row_mask:0xf bank_mask:0xf
	s_nop 1
	v_add_f32_dpp v160, v160, v160 quad_perm:[2,3,0,1] row_mask:0xf bank_mask:0xf
	s_nop 1
	v_add_f32_dpp v160, v160, v160 row_half_mirror row_mask:0xf bank_mask:0xf
	s_nop 1
	v_add_f32_dpp v160, v160, v160 row_mirror row_mask:0xf bank_mask:0xf
	s_nop 1
	v_add_f32_dpp v160, v160, v160 row_bcast:15 row_mask:0xa bank_mask:0xf
	s_nop 1
	v_add_f32_dpp v160, v160, v160 row_bcast:31 row_mask:0xc bank_mask:0xf
	s_nop 1
	v_readlane_b32 s0, v160, 63
	s_nop 2
	v_mov_b32_e32 v170, s0
	v_mul_f32_e32 v156, 0xba800000, v170
	v_mul_f32_e32 v157, 0xba800000, v170
	v_pk_add_f32 v[114:115], v[114:115], v[156:157]
	v_pk_add_f32 v[116:117], v[116:117], v[156:157]
	v_pk_add_f32 v[118:119], v[118:119], v[156:157]
	v_pk_add_f32 v[120:121], v[120:121], v[156:157]
	v_pk_add_f32 v[122:123], v[122:123], v[156:157]
	v_pk_add_f32 v[124:125], v[124:125], v[156:157]
	v_pk_add_f32 v[126:127], v[126:127], v[156:157]
	v_pk_add_f32 v[128:129], v[128:129], v[156:157]
	v_pk_mul_f32 v[154:155], v[114:115], v[114:115]
	v_pk_fma_f32 v[154:155], v[116:117], v[116:117], v[154:155]
	v_pk_fma_f32 v[154:155], v[118:119], v[118:119], v[154:155]
	v_pk_fma_f32 v[154:155], v[120:121], v[120:121], v[154:155]
	v_pk_fma_f32 v[154:155], v[122:123], v[122:123], v[154:155]
	v_pk_fma_f32 v[154:155], v[124:125], v[124:125], v[154:155]
	v_pk_fma_f32 v[154:155], v[126:127], v[126:127], v[154:155]
	v_pk_fma_f32 v[154:155], v[128:129], v[128:129], v[154:155]
	v_add_f32_e32 v154, v154, v155
	s_nop 1
	v_add_f32_dpp v160, v154, v154 quad_perm:[1,0,3,2] row_mask:0xf bank_mask:0xf
	s_nop 1
	v_add_f32_dpp v160, v160, v160 quad_perm:[2,3,0,1] row_mask:0xf bank_mask:0xf
	s_nop 1
	v_add_f32_dpp v160, v160, v160 row_half_mirror row_mask:0xf bank_mask:0xf
	s_nop 1
	v_add_f32_dpp v160, v160, v160 row_mirror row_mask:0xf bank_mask:0xf
	s_nop 1
	v_add_f32_dpp v160, v160, v160 row_bcast:15 row_mask:0xa bank_mask:0xf
	s_nop 1
	v_add_f32_dpp v160, v160, v160 row_bcast:31 row_mask:0xc bank_mask:0xf
	s_nop 1
	v_readlane_b32 s0, v160, 63
	s_nop 2
	v_mov_b32_e32 v170, s0
	v_fmamk_f32 v154, v170, 0x3a800000, v166
	s_mov_b32 s0, 0xf800000
	v_mul_f32_e32 v155, 0x4f800000, v154
	v_cmp_gt_f32_e32 vcc, s0, v154
	s_nop 1
	v_cndmask_b32_e32 v154, v154, v155, vcc
	v_sqrt_f32_e32 v155, v154
	s_nop 0
	v_add_u32_e32 v156, -1, v155
	v_fma_f32 v157, -v156, v155, v154
	v_cmp_ge_f32_e64 s[0:1], 0, v157
	v_add_u32_e32 v157, 1, v155
	s_nop 0
	v_cndmask_b32_e64 v156, v155, v156, s[0:1]
	v_fma_f32 v155, -v157, v155, v154
	v_cmp_lt_f32_e64 s[0:1], 0, v155
	s_nop 1
	v_cndmask_b32_e64 v155, v156, v157, s[0:1]
	v_mul_f32_e32 v156, 0x37800000, v155
; __device__ __forceinline__ unsigned pk2(float lo, float hi) { return pg8::cvt_pk_bf16(lo, hi); }
; __device__ __forceinline__ float bflo(unsigned u) { return __uint_as_float(u << 16); }
; __device__ __forceinline__ float bfhi(unsigned u) { return __uint_as_float(u & 0xffff0000u); }
; __device__ __forceinline__ void ln_panel(int pm, const float* resf, const bf16* rlo, const bf16* dlt, float* xo, const float* gam, const float* bet, bf16* xb, bf16* wlo, bool fin, float alpha) {
;     ...
;         for (int j = 0; j < 4; ++j) { f32x4 x; const u32x2 d = *(const u32x2*)(dlt + prow + 256 * j);
;             if (resf) x = *(const f32x4*)(resf + grow + 256 * j);
;             else { const u32x2 h = *(const u32x2*)(xb + grow + 256 * j), l = *(const u32x2*)(rlo + prow + 256 * j);
;     ...
;         const float rstd = 1.f / sqrtf(wave_sum(s2) * (1.f / DM) + LN_EPS);
; #pragma unroll
;         for (int j = 0; j < 4; ++j) { const f32x4 o = v[j] * rstd * gv[j] + bv[j];
;             if (fin) *(f32x4*)(xo + grow + 256 * j) = o;
;             else { u32x2 w; w.x = pk2(o.x, o.y); w.y = pk2(o.z, o.w); *(u32x2*)(xb + grow + 256 * j) = w;
;                    u32x2 q; q.x = pk2(o.x - bflo(w.x), o.y - bfhi(w.x)); q.y = pk2(o.z - bflo(w.y), o.w - bfhi(w.y)); *(u32x2*)(wlo + prow + 256 * j) = q; } }
	v_cndmask_b32_e32 v155, v155, v156, vcc
	v_cmp_class_f32_e32 vcc, v154, v167
	s_nop 1
	v_cndmask_b32_e32 v154, v155, v154, vcc
	v_div_scale_f32 v155, s[0:1], v154, v154, 1.0
	v_rcp_f32_e32 v156, v155
	s_nop 0
	v_fma_f32 v157, -v155, v156, 1.0
	v_fmac_f32_e32 v156, v157, v156
	v_div_scale_f32 v157, vcc, 1.0, v154, 1.0
	v_mul_f32_e32 v158, v157, v156
	v_fma_f32 v159, -v155, v158, v157
	v_fmac_f32_e32 v158, v159, v156
	v_fma_f32 v155, -v155, v158, v157
	s_nop 0
	v_div_fmas_f32 v155, v155, v156, v158
	v_div_fixup_f32 v168, v155, v154, 1.0
	s_add_i32 s0, s98, 0
	s_lshl_b32 s0, s0, 11
	s_mov_b32 s1, 0
	v_lshl_add_u64 v[184:185], s[0:1], 0, v[172:173]
	v_lshl_add_u64 v[186:187], s[0:1], 0, v[180:181]
	v_pk_mul_f32 v[150:151], v[114:115], v[168:169] op_sel_hi:[1,0]
	v_pk_fma_f32 v[150:151], v[0:1], v[150:151], v[8:9]
	v_pk_mul_f32 v[152:153], v[116:117], v[168:169] op_sel_hi:[1,0]
	v_pk_fma_f32 v[152:153], v[2:3], v[152:153], v[10:11]
	v_cvt_pk_bf16_f32 v190, v150, v151
	v_cvt_pk_bf16_f32 v191, v152, v153
	v_lshlrev_b32_e32 v154, 16, v190
	v_and_b32_e32 v155, 0xffff0000, v190
	v_pk_add_f32 v[150:151], v[150:151], v[154:155] neg_lo:[0,1] neg_hi:[0,1]
	v_cvt_pk_bf16_f32 v198, v150, v151
	v_lshlrev_b32_e32 v154, 16, v191
	v_and_b32_e32 v155, 0xffff0000, v191
	v_pk_add_f32 v[152:153], v[152:153], v[154:155] neg_lo:[0,1] neg_hi:[0,1]
	v_cvt_pk_bf16_f32 v199, v152, v153
	v_pk_mul_f32 v[150:151], v[118:119], v[168:169] op_sel_hi:[1,0]
	v_pk_fma_f32 v[150:151], v[4:5], v[150:151], v[12:13]
	v_pk_mul_f32 v[152:153], v[120:121], v[168:169] op_sel_hi:[1,0]
	v_pk_fma_f32 v[152:153], v[6:7], v[152:153], v[14:15]
	v_cvt_pk_bf16_f32 v192, v150, v151
	v_cvt_pk_bf16_f32 v193, v152, v153
	v_lshlrev_b32_e32 v154, 16, v192
	v_and_b32_e32 v155, 0xffff0000, v192
	v_pk_add_f32 v[150:151], v[150:151], v[154:155] neg_lo:[0,1] neg_hi:[0,1]
	v_cvt_pk_bf16_f32 v200, v150, v151
	v_lshlrev_b32_e32 v154, 16, v193
	v_and_b32_e32 v155, 0xffff0000, v193
	v_pk_add_f32 v[152:153], v[152:153], v[154:155] neg_lo:[0,1] neg_hi:[0,1]
	v_cvt_pk_bf16_f32 v201, v152, v153
	v_pk_mul_f32 v[150:151], v[122:123], v[168:169] op_sel_hi:[1,0]
	v_pk_fma_f32 v[150:151], v[16:17], v[150:151], v[24:25]
	v_pk_mul_f32 v[152:153], v[124:125], v[168:169] op_sel_hi:[1,0]
	v_pk_fma_f32 v[152:153], v[18:19], v[152:153], v[26:27]
	v_cvt_pk_bf16_f32 v194, v150, v151
	v_cvt_pk_bf16_f32 v195, v152, v153
	v_lshlrev_b32_e32 v154, 16, v194
	v_and_b32_e32 v155, 0xffff0000, v194
	v_pk_add_f32 v[150:151], v[150:151], v[154:155] neg_lo:[0,1] neg_hi:[0,1]
	v_cvt_pk_bf16_f32 v202, v150, v151
	v_lshlrev_b32_e32 v154, 16, v195
	v_and_b32_e32 v155, 0xffff0000, v195
	v_pk_add_f32 v[152:153], v[152:153], v[154:155] neg_lo:[0,1] neg_hi:[0,1]
	v_cvt_pk_bf16_f32 v203, v152, v153
	v_pk_mul_f32 v[150:151], v[126:127], v[168:169] op_sel_hi:[1,0]
	v_pk_fma_f32 v[150:151], v[20:21], v[150:151], v[28:29]
	v_pk_mul_f32 v[152:153], v[128:129], v[168:169] op_sel_hi:[1,0]
	v_pk_fma_f32 v[152:153], v[22:23], v[152:153], v[30:31]
	v_cvt_pk_bf16_f32 v196, v150, v151
	v_cvt_pk_bf16_f32 v197, v152, v153
	v_lshlrev_b32_e32 v154, 16, v196
	v_and_b32_e32 v155, 0xffff0000, v196
	v_pk_add_f32 v[150:151], v[150:151], v[154:155] neg_lo:[0,1] neg_hi:[0,1]
	v_cvt_pk_bf16_f32 v204, v150, v151
	v_lshlrev_b32_e32 v154, 16, v197
	v_and_b32_e32 v155, 0xffff0000, v197
	v_pk_add_f32 v[152:153], v[152:153], v[154:155] neg_lo:[0,1] neg_hi:[0,1]
	v_cvt_pk_bf16_f32 v205, v152, v153
	global_store_dwordx2 v[184:185], v[190:191], off offset:0
	global_store_dwordx2 v[184:185], v[192:193], off offset:512
	global_store_dwordx2 v[184:185], v[194:195], off offset:1024
	global_store_dwordx2 v[184:185], v[196:197], off offset:1536
	global_store_dwordx2 v[186:187], v[198:199], off offset:0
	global_store_dwordx2 v[186:187], v[200:201], off offset:512
	global_store_dwordx2 v[186:187], v[202:203], off offset:1024
	global_store_dwordx2 v[186:187], v[204:205], off offset:1536
	s_add_i32 s0, s98, 2
	s_min_u32 s0, s0, 31
	s_lshl_b32 s0, s0, 11
	s_mov_b32 s1, 0
	v_lshl_add_u64 v[184:185], s[0:1], 0, v[178:179]
	v_lshl_add_u64 v[186:187], s[0:1], 0, v[172:173]
	v_lshl_add_u64 v[188:189], s[0:1], 0, v[176:177]
	global_load_dwordx2 v[82:83], v[184:185], off offset:-1024 nt
	global_load_dwordx2 v[84:85], v[184:185], off offset:-512 nt
	global_load_dwordx2 v[86:87], v[184:185], off offset:0 nt
	global_load_dwordx2 v[88:89], v[184:185], off offset:512 nt
	global_load_dwordx2 v[66:67], v[186:187], off offset:0
	global_load_dwordx2 v[68:69], v[186:187], off offset:512
	global_load_dwordx2 v[70:71], v[186:187], off offset:1024
	global_load_dwordx2 v[72:73], v[186:187], off offset:1536
	global_load_dwordx2 v[74:75], v[188:189], off offset:0 nt
	global_load_dwordx2 v[76:77], v[188:189], off offset:512 nt
	global_load_dwordx2 v[78:79], v[188:189], off offset:1024 nt
	global_load_dwordx2 v[80:81], v[188:189], off offset:1536 nt
	s_waitcnt vmcnt(20)
; __device__ __forceinline__ float bflo(unsigned u) { return __uint_as_float(u << 16); }
; __device__ __forceinline__ float bfhi(unsigned u) { return __uint_as_float(u & 0xffff0000u); }
; __device__ __forceinline__ void ln_panel(int pm, const float* resf, const bf16* rlo, const bf16* dlt, float* xo, const float* gam, const float* bet, bf16* xb, bf16* wlo, bool fin, float alpha) {
;     ...
;         for (int j = 0; j < 4; ++j) { f32x4 x; const u32x2 d = *(const u32x2*)(dlt + prow + 256 * j);
;             if (resf) x = *(const f32x4*)(resf + grow + 256 * j);
;             else { const u32x2 h = *(const u32x2*)(xb + grow + 256 * j), l = *(const u32x2*)(rlo + prow + 256 * j);
;                    x = (f32x4){bflo(h.x) + bflo(l.x), bfhi(h.x) + bfhi(l.x), bflo(h.y) + bflo(l.y), bfhi(h.y) + bfhi(l.y)}; }
;             v[j] = (f32x4){x.x * alpha + bflo(d.x), x.y * alpha + bfhi(d.x), x.z * alpha + bflo(d.y), x.w * alpha + bfhi(d.y)}; s += (v[j].x + v[j].y) + (v[j].z + v[j].w); }
;         const float mean = wave_sum(s) * (1.f / DM); float s2 = 0.f;
; #pragma unroll
;         for (int j = 0; j < 4; ++j) { v[j] = v[j] - mean; s2 += (v[j].x * v[j].x + v[j].y * v[j].y) + (v[j].z * v[j].z + v[j].w * v[j].w); }
;         const float rstd = 1.f / sqrtf(wave_sum(s2) * (1.f / DM) + LN_EPS);
	v_lshlrev_b32_e32 v150, 16, v90
	v_and_b32_e32 v151, 0xffff0000, v90
	v_lshlrev_b32_e32 v152, 16, v98
	v_and_b32_e32 v153, 0xffff0000, v98
	v_pk_add_f32 v[150:151], v[150:151], v[152:153]
	v_lshlrev_b32_e32 v152, 16, v106
	v_and_b32_e32 v153, 0xffff0000, v106
	v_pk_fma_f32 v[114:115], v[150:151], v[164:165], v[152:153]
	v_lshlrev_b32_e32 v150, 16, v91
	v_and_b32_e32 v151, 0xffff0000, v91
	v_lshlrev_b32_e32 v152, 16, v99
	v_and_b32_e32 v153, 0xffff0000, v99
	v_pk_add_f32 v[150:151], v[150:151], v[152:153]
	v_lshlrev_b32_e32 v152, 16, v107
	v_and_b32_e32 v153, 0xffff0000, v107
	v_pk_fma_f32 v[116:117], v[150:151], v[164:165], v[152:153]
	v_lshlrev_b32_e32 v150, 16, v92
	v_and_b32_e32 v151, 0xffff0000, v92
	v_lshlrev_b32_e32 v152, 16, v100
	v_and_b32_e32 v153, 0xffff0000, v100
	v_pk_add_f32 v[150:151], v[150:151], v[152:153]
	v_lshlrev_b32_e32 v152, 16, v108
	v_and_b32_e32 v153, 0xffff0000, v108
	v_pk_fma_f32 v[118:119], v[150:151], v[164:165], v[152:153]
	v_lshlrev_b32_e32 v150, 16, v93
	v_and_b32_e32 v151, 0xffff0000, v93
	v_lshlrev_b32_e32 v152, 16, v101
	v_and_b32_e32 v153, 0xffff0000, v101
	v_pk_add_f32 v[150:151], v[150:151], v[152:153]
	v_lshlrev_b32_e32 v152, 16, v109
	v_and_b32_e32 v153, 0xffff0000, v109
	v_pk_fma_f32 v[120:121], v[150:151], v[164:165], v[152:153]
	v_lshlrev_b32_e32 v150, 16, v94
	v_and_b32_e32 v151, 0xffff0000, v94
	v_lshlrev_b32_e32 v152, 16, v102
	v_and_b32_e32 v153, 0xffff0000, v102
	v_pk_add_f32 v[150:151], v[150:151], v[152:153]
	v_lshlrev_b32_e32 v152, 16, v110
	v_and_b32_e32 v153, 0xffff0000, v110
	v_pk_fma_f32 v[122:123], v[150:151], v[164:165], v[152:153]
	v_lshlrev_b32_e32 v150, 16, v95
	v_and_b32_e32 v151, 0xffff0000, v95
	v_lshlrev_b32_e32 v152, 16, v103
	v_and_b32_e32 v153, 0xffff0000, v103
	v_pk_add_f32 v[150:151], v[150:151], v[152:153]
	v_lshlrev_b32_e32 v152, 16, v111
	v_and_b32_e32 v153, 0xffff0000, v111
	v_pk_fma_f32 v[124:125], v[150:151], v[164:165], v[152:153]
	v_lshlrev_b32_e32 v150, 16, v96
	v_and_b32_e32 v151, 0xffff0000, v96
	v_lshlrev_b32_e32 v152, 16, v104
	v_and_b32_e32 v153, 0xffff0000, v104
	v_pk_add_f32 v[150:151], v[150:151], v[152:153]
	v_lshlrev_b32_e32 v152, 16, v112
	v_and_b32_e32 v153, 0xffff0000, v112
	v_pk_fma_f32 v[126:127], v[150:151], v[164:165], v[152:153]
	v_lshlrev_b32_e32 v150, 16, v97
	v_and_b32_e32 v151, 0xffff0000, v97
	v_lshlrev_b32_e32 v152, 16, v105
	v_and_b32_e32 v153, 0xffff0000, v105
	v_pk_add_f32 v[150:151], v[150:151], v[152:153]
	v_lshlrev_b32_e32 v152, 16, v113
	v_and_b32_e32 v153, 0xffff0000, v113
	v_pk_fma_f32 v[128:129], v[150:151], v[164:165], v[152:153]
	v_pk_add_f32 v[154:155], v[114:115], v[116:117]
	v_pk_add_f32 v[156:157], v[118:119], v[120:121]
	v_pk_add_f32 v[154:155], v[154:155], v[156:157]
	v_pk_add_f32 v[156:157], v[122:123], v[124:125]
	v_pk_add_f32 v[154:155], v[154:155], v[156:157]
	v_pk_add_f32 v[156:157], v[126:127], v[128:129]
	v_pk_add_f32 v[154:155], v[154:155], v[156:157]
	v_add_f32_e32 v154, v154, v155
	s_nop 1
	v_add_f32_dpp v160, v154, v154 quad_perm:[1,0,3,2] row_mask:0xf bank_mask:0xf
	s_nop 1
	v_add_f32_dpp v160, v160, v160 quad_perm:[2,3,0,1] row_mask:0xf bank_mask:0xf
	s_nop 1
	v_add_f32_dpp v160, v160, v160 row_half_mirror row_mask:0xf bank_mask:0xf
	s_nop 1
	v_add_f32_dpp v160, v160, v160 row_mirror row_mask:0xf bank_mask:0xf
	s_nop 1
	v_add_f32_dpp v160, v160, v160 row_bcast:15 row_mask:0xa bank_mask:0xf
	s_nop 1
	v_add_f32_dpp v160, v160, v160 row_bcast:31 row_mask:0xc bank_mask:0xf
	s_nop 1
	v_readlane_b32 s0, v160, 63
	s_nop 2
	v_mov_b32_e32 v170, s0
	v_mul_f32_e32 v156, 0xba800000, v170
	v_mul_f32_e32 v157, 0xba800000, v170
	v_pk_add_f32 v[114:115], v[114:115], v[156:157]
	v_pk_add_f32 v[116:117], v[116:117], v[156:157]
	v_pk_add_f32 v[118:119], v[118:119], v[156:157]
	v_pk_add_f32 v[120:121], v[120:121], v[156:157]
	v_pk_add_f32 v[122:123], v[122:123], v[156:157]
	v_pk_add_f32 v[124:125], v[124:125], v[156:157]
	v_pk_add_f32 v[126:127], v[126:127], v[156:157]
	v_pk_add_f32 v[128:129], v[128:129], v[156:157]
	v_pk_mul_f32 v[154:155], v[114:115], v[114:115]
	v_pk_fma_f32 v[154:155], v[116:117], v[116:117], v[154:155]
	v_pk_fma_f32 v[154:155], v[118:119], v[118:119], v[154:155]
	v_pk_fma_f32 v[154:155], v[120:121], v[120:121], v[154:155]
	v_pk_fma_f32 v[154:155], v[122:123], v[122:123], v[154:155]
	v_pk_fma_f32 v[154:155], v[124:125], v[124:125], v[154:155]
	v_pk_fma_f32 v[154:155], v[126:127], v[126:127], v[154:155]
	v_pk_fma_f32 v[154:155], v[128:129], v[128:129], v[154:155]
	v_add_f32_e32 v154, v154, v155
	s_nop 1
	v_add_f32_dpp v160, v154, v154 quad_perm:[1,0,3,2] row_mask:0xf bank_mask:0xf
	s_nop 1
	v_add_f32_dpp v160, v160, v160 quad_perm:[2,3,0,1] row_mask:0xf bank_mask:0xf
	s_nop 1
	v_add_f32_dpp v160, v160, v160 row_half_mirror row_mask:0xf bank_mask:0xf
	s_nop 1
	v_add_f32_dpp v160, v160, v160 row_mirror row_mask:0xf bank_mask:0xf
	s_nop 1
	v_add_f32_dpp v160, v160, v160 row_bcast:15 row_mask:0xa bank_mask:0xf
	s_nop 1
	v_add_f32_dpp v160, v160, v160 row_bcast:31 row_mask:0xc bank_mask:0xf
	s_nop 1
	v_readlane_b32 s0, v160, 63
	s_nop 2
	v_mov_b32_e32 v170, s0
	v_fmamk_f32 v154, v170, 0x3a800000, v166
	s_mov_b32 s0, 0xf800000
	v_mul_f32_e32 v155, 0x4f800000, v154
	v_cmp_gt_f32_e32 vcc, s0, v154
	s_nop 1
	v_cndmask_b32_e32 v154, v154, v155, vcc
	v_sqrt_f32_e32 v155, v154
	s_nop 0
	v_add_u32_e32 v156, -1, v155
	v_fma_f32 v157, -v156, v155, v154
	v_cmp_ge_f32_e64 s[0:1], 0, v157
	v_add_u32_e32 v157, 1, v155
	s_nop 0
	v_cndmask_b32_e64 v156, v155, v156, s[0:1]
	v_fma_f32 v155, -v157, v155, v154
	v_cmp_lt_f32_e64 s[0:1], 0, v155
	s_nop 1
	v_cndmask_b32_e64 v155, v156, v157, s[0:1]
	v_mul_f32_e32 v156, 0x37800000, v155
; __device__ __forceinline__ unsigned pk2(float lo, float hi) { return pg8::cvt_pk_bf16(lo, hi); }
; __device__ __forceinline__ float bflo(unsigned u) { return __uint_as_float(u << 16); }
; __device__ __forceinline__ float bfhi(unsigned u) { return __uint_as_float(u & 0xffff0000u); }
; __device__ __forceinline__ void ln_panel(int pm, const float* resf, const bf16* rlo, const bf16* dlt, float* xo, const float* gam, const float* bet, bf16* xb, bf16* wlo, bool fin, float alpha) {
;     ...
;         for (int j = 0; j < 4; ++j) { f32x4 x; const u32x2 d = *(const u32x2*)(dlt + prow + 256 * j);
;             if (resf) x = *(const f32x4*)(resf + grow + 256 * j);
;             else { const u32x2 h = *(const u32x2*)(xb + grow + 256 * j), l = *(const u32x2*)(rlo + prow + 256 * j);
;                    x = (f32x4){bflo(h.x) + bflo(l.x), bfhi(h.x) + bfhi(l.x), bflo(h.y) + bflo(l.y), bfhi(h.y) + bfhi(l.y)}; }
;     ...
;         const float rstd = 1.f / sqrtf(wave_sum(s2) * (1.f / DM) + LN_EPS);
; #pragma unroll
;         for (int j = 0; j < 4; ++j) { const f32x4 o = v[j] * rstd * gv[j] + bv[j];
;             if (fin) *(f32x4*)(xo + grow + 256 * j) = o;
;             else { u32x2 w; w.x = pk2(o.x, o.y); w.y = pk2(o.z, o.w); *(u32x2*)(xb + grow + 256 * j) = w;
;                    u32x2 q; q.x = pk2(o.x - bflo(w.x), o.y - bfhi(w.x)); q.y = pk2(o.z - bflo(w.y), o.w - bfhi(w.y)); *(u32x2*)(wlo + prow + 256 * j) = q; } }
	v_cndmask_b32_e32 v155, v155, v156, vcc
	v_cmp_class_f32_e32 vcc, v154, v167
	s_nop 1
	v_cndmask_b32_e32 v154, v155, v154, vcc
	v_div_scale_f32 v155, s[0:1], v154, v154, 1.0
	v_rcp_f32_e32 v156, v155
	s_nop 0
	v_fma_f32 v157, -v155, v156, 1.0
	v_fmac_f32_e32 v156, v157, v156
	v_div_scale_f32 v157, vcc, 1.0, v154, 1.0
	v_mul_f32_e32 v158, v157, v156
	v_fma_f32 v159, -v155, v158, v157
	v_fmac_f32_e32 v158, v159, v156
	v_fma_f32 v155, -v155, v158, v157
	s_nop 0
	v_div_fmas_f32 v155, v155, v156, v158
	v_div_fixup_f32 v168, v155, v154, 1.0
	s_add_i32 s0, s98, 1
	s_lshl_b32 s0, s0, 11
	s_mov_b32 s1, 0
	v_lshl_add_u64 v[184:185], s[0:1], 0, v[172:173]
	v_lshl_add_u64 v[186:187], s[0:1], 0, v[180:181]
	v_pk_mul_f32 v[150:151], v[114:115], v[168:169] op_sel_hi:[1,0]
	v_pk_fma_f32 v[150:151], v[0:1], v[150:151], v[8:9]
	v_pk_mul_f32 v[152:153], v[116:117], v[168:169] op_sel_hi:[1,0]
	v_pk_fma_f32 v[152:153], v[2:3], v[152:153], v[10:11]
	v_cvt_pk_bf16_f32 v190, v150, v151
	v_cvt_pk_bf16_f32 v191, v152, v153
	v_lshlrev_b32_e32 v154, 16, v190
	v_and_b32_e32 v155, 0xffff0000, v190
	v_pk_add_f32 v[150:151], v[150:151], v[154:155] neg_lo:[0,1] neg_hi:[0,1]
	v_cvt_pk_bf16_f32 v198, v150, v151
	v_lshlrev_b32_e32 v154, 16, v191
	v_and_b32_e32 v155, 0xffff0000, v191
	v_pk_add_f32 v[152:153], v[152:153], v[154:155] neg_lo:[0,1] neg_hi:[0,1]
	v_cvt_pk_bf16_f32 v199, v152, v153
	v_pk_mul_f32 v[150:151], v[118:119], v[168:169] op_sel_hi:[1,0]
	v_pk_fma_f32 v[150:151], v[4:5], v[150:151], v[12:13]
	v_pk_mul_f32 v[152:153], v[120:121], v[168:169] op_sel_hi:[1,0]
	v_pk_fma_f32 v[152:153], v[6:7], v[152:153], v[14:15]
	v_cvt_pk_bf16_f32 v192, v150, v151
	v_cvt_pk_bf16_f32 v193, v152, v153
	v_lshlrev_b32_e32 v154, 16, v192
	v_and_b32_e32 v155, 0xffff0000, v192
	v_pk_add_f32 v[150:151], v[150:151], v[154:155] neg_lo:[0,1] neg_hi:[0,1]
	v_cvt_pk_bf16_f32 v200, v150, v151
	v_lshlrev_b32_e32 v154, 16, v193
	v_and_b32_e32 v155, 0xffff0000, v193
	v_pk_add_f32 v[152:153], v[152:153], v[154:155] neg_lo:[0,1] neg_hi:[0,1]
	v_cvt_pk_bf16_f32 v201, v152, v153
	v_pk_mul_f32 v[150:151], v[122:123], v[168:169] op_sel_hi:[1,0]
	v_pk_fma_f32 v[150:151], v[16:17], v[150:151], v[24:25]
	v_pk_mul_f32 v[152:153], v[124:125], v[168:169] op_sel_hi:[1,0]
	v_pk_fma_f32 v[152:153], v[18:19], v[152:153], v[26:27]
	v_cvt_pk_bf16_f32 v194, v150, v151
	v_cvt_pk_bf16_f32 v195, v152, v153
	v_lshlrev_b32_e32 v154, 16, v194
	v_and_b32_e32 v155, 0xffff0000, v194
	v_pk_add_f32 v[150:151], v[150:151], v[154:155] neg_lo:[0,1] neg_hi:[0,1]
	v_cvt_pk_bf16_f32 v202, v150, v151
	v_lshlrev_b32_e32 v154, 16, v195
	v_and_b32_e32 v155, 0xffff0000, v195
	v_pk_add_f32 v[152:153], v[152:153], v[154:155] neg_lo:[0,1] neg_hi:[0,1]
	v_cvt_pk_bf16_f32 v203, v152, v153
	v_pk_mul_f32 v[150:151], v[126:127], v[168:169] op_sel_hi:[1,0]
	v_pk_fma_f32 v[150:151], v[20:21], v[150:151], v[28:29]
	v_pk_mul_f32 v[152:153], v[128:129], v[168:169] op_sel_hi:[1,0]
	v_pk_fma_f32 v[152:153], v[22:23], v[152:153], v[30:31]
	v_cvt_pk_bf16_f32 v196, v150, v151
	v_cvt_pk_bf16_f32 v197, v152, v153
	v_lshlrev_b32_e32 v154, 16, v196
	v_and_b32_e32 v155, 0xffff0000, v196
	v_pk_add_f32 v[150:151], v[150:151], v[154:155] neg_lo:[0,1] neg_hi:[0,1]
	v_cvt_pk_bf16_f32 v204, v150, v151
	v_lshlrev_b32_e32 v154, 16, v197
	v_and_b32_e32 v155, 0xffff0000, v197
	v_pk_add_f32 v[152:153], v[152:153], v[154:155] neg_lo:[0,1] neg_hi:[0,1]
	v_cvt_pk_bf16_f32 v205, v152, v153
	global_store_dwordx2 v[184:185], v[190:191], off offset:0
	global_store_dwordx2 v[184:185], v[192:193], off offset:512
	global_store_dwordx2 v[184:185], v[194:195], off offset:1024
	global_store_dwordx2 v[184:185], v[196:197], off offset:1536
	global_store_dwordx2 v[186:187], v[198:199], off offset:0
	global_store_dwordx2 v[186:187], v[200:201], off offset:512
	global_store_dwordx2 v[186:187], v[202:203], off offset:1024
	global_store_dwordx2 v[186:187], v[204:205], off offset:1536
	s_add_i32 s0, s98, 3
	s_min_u32 s0, s0, 31
	s_lshl_b32 s0, s0, 11
	s_mov_b32 s1, 0
	v_lshl_add_u64 v[184:185], s[0:1], 0, v[178:179]
	v_lshl_add_u64 v[186:187], s[0:1], 0, v[172:173]
	v_lshl_add_u64 v[188:189], s[0:1], 0, v[176:177]
	global_load_dwordx2 v[106:107], v[184:185], off offset:-1024 nt
	global_load_dwordx2 v[108:109], v[184:185], off offset:-512 nt
	global_load_dwordx2 v[110:111], v[184:185], off offset:0 nt
	global_load_dwordx2 v[112:113], v[184:185], off offset:512 nt
	global_load_dwordx2 v[90:91], v[186:187], off offset:0
	global_load_dwordx2 v[92:93], v[186:187], off offset:512
	global_load_dwordx2 v[94:95], v[186:187], off offset:1024
	global_load_dwordx2 v[96:97], v[186:187], off offset:1536
	global_load_dwordx2 v[98:99], v[188:189], off offset:0 nt
	global_load_dwordx2 v[100:101], v[188:189], off offset:512 nt
	global_load_dwordx2 v[102:103], v[188:189], off offset:1024 nt
	global_load_dwordx2 v[104:105], v[188:189], off offset:1536 nt
	s_add_i32 s98, s98, 2
	s_cmp_lt_u32 s98, 32
	s_cbranch_scc1 .Lmy_ln1h_loop
	s_waitcnt vmcnt(0)
	s_branch .LBB0_557
.Lmy_ln1r_start:
	s_mov_b32 s98, 0
	s_add_i32 s0, s98, 0
	s_min_u32 s0, s0, 31
	s_lshl_b32 s0, s0, 11
	s_mov_b32 s1, 0
	v_lshl_add_u64 v[184:185], s[0:1], 0, v[178:179]
	v_lshl_add_u64 v[186:187], s[0:1], 1, v[182:183]
	global_load_dwordx2 v[82:83], v[184:185], off offset:-1024 nt
	global_load_dwordx2 v[84:85], v[184:185], off offset:-512 nt
	global_load_dwordx2 v[86:87], v[184:185], off offset:0 nt
	global_load_dwordx2 v[88:89], v[184:185], off offset:512 nt
	global_load_dwordx4 v[66:69], v[186:187], off offset:0 nt
	global_load_dwordx4 v[70:73], v[186:187], off offset:1024 nt
	global_load_dwordx4 v[74:77], v[186:187], off offset:2048 nt
	global_load_dwordx4 v[78:81], v[186:187], off offset:3072 nt
	s_add_i32 s0, s98, 1
	s_min_u32 s0, s0, 31
	s_lshl_b32 s0, s0, 11
	s_mov_b32 s1, 0
	v_lshl_add_u64 v[184:185], s[0:1], 0, v[178:179]
	v_lshl_add_u64 v[186:187], s[0:1], 1, v[182:183]
	global_load_dwordx2 v[106:107], v[184:185], off offset:-1024 nt
	global_load_dwordx2 v[108:109], v[184:185], off offset:-512 nt
	global_load_dwordx2 v[110:111], v[184:185], off offset:0 nt
	global_load_dwordx2 v[112:113], v[184:185], off offset:512 nt
	global_load_dwordx4 v[90:93], v[186:187], off offset:0 nt
	global_load_dwordx4 v[94:97], v[186:187], off offset:1024 nt
	global_load_dwordx4 v[98:101], v[186:187], off offset:2048 nt
	global_load_dwordx4 v[102:105], v[186:187], off offset:3072 nt
	s_waitcnt vmcnt(8)
	s_branch .Lmy_ln1r_entry

; __device__ __forceinline__ unsigned pk2(float lo, float hi) { return pg8::cvt_pk_bf16(lo, hi); }
; __device__ __forceinline__ float bflo(unsigned u) { return __uint_as_float(u << 16); }
; __device__ __forceinline__ float bfhi(unsigned u) { return __uint_as_float(u & 0xffff0000u); }
; __device__ __forceinline__ void ln_panel(int pm, const float* resf, const bf16* rlo, const bf16* dlt, float* xo, const float* gam, const float* bet, bf16* xb, bf16* wlo, bool fin, float alpha) {
;     ...
;         for (int j = 0; j < 4; ++j) { f32x4 x; const u32x2 d = *(const u32x2*)(dlt + prow + 256 * j);
;             if (resf) x = *(const f32x4*)(resf + grow + 256 * j);
;             else { const u32x2 h = *(const u32x2*)(xb + grow + 256 * j), l = *(const u32x2*)(rlo + prow + 256 * j);
;                    x = (f32x4){bflo(h.x) + bflo(l.x), bfhi(h.x) + bfhi(l.x), bflo(h.y) + bflo(l.y), bfhi(h.y) + bfhi(l.y)}; }
;             v[j] = (f32x4){x.x * alpha + bflo(d.x), x.y * alpha + bfhi(d.x), x.z * alpha + bflo(d.y), x.w * alpha + bfhi(d.y)}; s += (v[j].x + v[j].y) + (v[j].z + v[j].w); }
;         const float mean = wave_sum(s) * (1.f / DM); float s2 = 0.f;
; #pragma unroll
;         for (int j = 0; j < 4; ++j) { v[j] = v[j] - mean; s2 += (v[j].x * v[j].x + v[j].y * v[j].y) + (v[j].z * v[j].z + v[j].w * v[j].w); }
;         const float rstd = 1.f / sqrtf(wave_sum(s2) * (1.f / DM) + LN_EPS);
; #pragma unroll
;         for (int j = 0; j < 4; ++j) { const f32x4 o = v[j] * rstd * gv[j] + bv[j];
;             if (fin) *(f32x4*)(xo + grow + 256 * j) = o;
;             else { u32x2 w; w.x = pk2(o.x, o.y); w.y = pk2(o.z, o.w); *(u32x2*)(xb + grow + 256 * j) = w;
;                    u32x2 q; q.x = pk2(o.x - bflo(w.x), o.y - bfhi(w.x)); q.y = pk2(o.z - bflo(w.y), o.w - bfhi(w.y)); *(u32x2*)(wlo + prow + 256 * j) = q; } }
.Lmy_ln1r_entry:
	v_lshlrev_b32_e32 v152, 16, v82
	v_and_b32_e32 v153, 0xffff0000, v82
	v_pk_fma_f32 v[114:115], v[66:67], v[164:165], v[152:153]
	v_lshlrev_b32_e32 v152, 16, v83
	v_and_b32_e32 v153, 0xffff0000, v83
	v_pk_fma_f32 v[116:117], v[68:69], v[164:165], v[152:153]
	v_lshlrev_b32_e32 v152, 16, v84
	v_and_b32_e32 v153, 0xffff0000, v84
	v_pk_fma_f32 v[118:119], v[70:71], v[164:165], v[152:153]
	v_lshlrev_b32_e32 v152, 16, v85
	v_and_b32_e32 v153, 0xffff0000, v85
	v_pk_fma_f32 v[120:121], v[72:73], v[164:165], v[152:153]
	v_lshlrev_b32_e32 v152, 16, v86
	v_and_b32_e32 v153, 0xffff0000, v86
	v_pk_fma_f32 v[122:123], v[74:75], v[164:165], v[152:153]
	v_lshlrev_b32_e32 v152, 16, v87
	v_and_b32_e32 v153, 0xffff0000, v87
	v_pk_fma_f32 v[124:125], v[76:77], v[164:165], v[152:153]
	v_lshlrev_b32_e32 v152, 16, v88
	v_and_b32_e32 v153, 0xffff0000, v88
	v_pk_fma_f32 v[126:127], v[78:79], v[164:165], v[152:153]
	v_lshlrev_b32_e32 v152, 16, v89
	v_and_b32_e32 v153, 0xffff0000, v89
	v_pk_fma_f32 v[128:129], v[80:81], v[164:165], v[152:153]
	v_pk_add_f32 v[154:155], v[114:115], v[116:117]
	v_pk_add_f32 v[156:157], v[118:119], v[120:121]
	v_pk_add_f32 v[154:155], v[154:155], v[156:157]
	v_pk_add_f32 v[156:157], v[122:123], v[124:125]
	v_pk_add_f32 v[154:155], v[154:155], v[156:157]
	v_pk_add_f32 v[156:157], v[126:127], v[128:129]
	v_pk_add_f32 v[154:155], v[154:155], v[156:157]
	v_add_f32_e32 v154, v154, v155
	s_nop 1
	v_add_f32_dpp v160, v154, v154 quad_perm:[1,0,3,2] row_mask:0xf bank_mask:0xf
	s_nop 1
	v_add_f32_dpp v160, v160, v160 quad_perm:[2,3,0,1] row_mask:0xf bank_mask:0xf
	s_nop 1
	v_add_f32_dpp v160, v160, v160 row_half_mirror row_mask:0xf bank_mask:0xf
	s_nop 1
	v_add_f32_dpp v160, v160, v160 row_mirror row_mask:0xf bank_mask:0xf
	s_nop 1
	v_add_f32_dpp v160, v160, v160 row_bcast:15 row_mask:0xa bank_mask:0xf
	s_nop 1
	v_add_f32_dpp v160, v160, v160 row_bcast:31 row_mask:0xc bank_mask:0xf
	s_nop 1
	v_readlane_b32 s0, v160, 63
	s_nop 2
	v_mov_b32_e32 v170, s0
	v_mul_f32_e32 v156, 0xba800000, v170
	v_mul_f32_e32 v157, 0xba800000, v170
	v_pk_add_f32 v[114:115], v[114:115], v[156:157]
	v_pk_add_f32 v[116:117], v[116:117], v[156:157]
	v_pk_add_f32 v[118:119], v[118:119], v[156:157]
	v_pk_add_f32 v[120:121], v[120:121], v[156:157]
	v_pk_add_f32 v[122:123], v[122:123], v[156:157]
	v_pk_add_f32 v[124:125], v[124:125], v[156:157]
	v_pk_add_f32 v[126:127], v[126:127], v[156:157]
	v_pk_add_f32 v[128:129], v[128:129], v[156:157]
	v_pk_mul_f32 v[154:155], v[114:115], v[114:115]
	v_pk_fma_f32 v[154:155], v[116:117], v[116:117], v[154:155]
	v_pk_fma_f32 v[154:155], v[118:119], v[118:119], v[154:155]
	v_pk_fma_f32 v[154:155], v[120:121], v[120:121], v[154:155]
	v_pk_fma_f32 v[154:155], v[122:123], v[122:123], v[154:155]
	v_pk_fma_f32 v[154:155], v[124:125], v[124:125], v[154:155]
	v_pk_fma_f32 v[154:155], v[126:127], v[126:127], v[154:155]
	v_pk_fma_f32 v[154:155], v[128:129], v[128:129], v[154:155]
	v_add_f32_e32 v154, v154, v155
	s_nop 1
	v_add_f32_dpp v160, v154, v154 quad_perm:[1,0,3,2] row_mask:0xf bank_mask:0xf
	s_nop 1
	v_add_f32_dpp v160, v160, v160 quad_perm:[2,3,0,1] row_mask:0xf bank_mask:0xf
	s_nop 1
	v_add_f32_dpp v160, v160, v160 row_half_mirror row_mask:0xf bank_mask:0xf
	s_nop 1
	v_add_f32_dpp v160, v160, v160 row_mirror row_mask:0xf bank_mask:0xf
	s_nop 1
	v_add_f32_dpp v160, v160, v160 row_bcast:15 row_mask:0xa bank_mask:0xf
	s_nop 1
	v_add_f32_dpp v160, v160, v160 row_bcast:31 row_mask:0xc bank_mask:0xf
	s_nop 1
	v_readlane_b32 s0, v160, 63
	s_nop 2
	v_mov_b32_e32 v170, s0
	v_fmamk_f32 v154, v170, 0x3a800000, v166
	s_mov_b32 s0, 0xf800000
	v_mul_f32_e32 v155, 0x4f800000, v154
	v_cmp_gt_f32_e32 vcc, s0, v154
	s_nop 1
	v_cndmask_b32_e32 v154, v154, v155, vcc
	v_sqrt_f32_e32 v155, v154
	s_nop 0
	v_add_u32_e32 v156, -1, v155
	v_fma_f32 v157, -v156, v155, v154
	v_cmp_ge_f32_e64 s[0:1], 0, v157
	v_add_u32_e32 v157, 1, v155
	s_nop 0
	v_cndmask_b32_e64 v156, v155, v156, s[0:1]
	v_fma_f32 v155, -v157, v155, v154
	v_cmp_lt_f32_e64 s[0:1], 0, v155
	s_nop 1
	v_cndmask_b32_e64 v155, v156, v157, s[0:1]
	v_mul_f32_e32 v156, 0x37800000, v155
	v_cndmask_b32_e32 v155, v155, v156, vcc
	v_cmp_class_f32_e32 vcc, v154, v167
	s_nop 1
	v_cndmask_b32_e32 v154, v155, v154, vcc
	v_div_scale_f32 v155, s[0:1], v154, v154, 1.0
	v_rcp_f32_e32 v156, v155
	s_nop 0
	v_fma_f32 v157, -v155, v156, 1.0
	v_fmac_f32_e32 v156, v157, v156
	v_div_scale_f32 v157, vcc, 1.0, v154, 1.0
	v_mul_f32_e32 v158, v157, v156
	v_fma_f32 v159, -v155, v158, v157
	v_fmac_f32_e32 v158, v159, v156
	v_fma_f32 v155, -v155, v158, v157
	s_nop 0
	v_div_fmas_f32 v155, v155, v156, v158
	v_div_fixup_f32 v168, v155, v154, 1.0
	s_add_i32 s0, s98, 0
	s_lshl_b32 s0, s0, 11
	s_mov_b32 s1, 0
	v_lshl_add_u64 v[184:185], s[0:1], 0, v[172:173]
	v_lshl_add_u64 v[186:187], s[0:1], 0, v[180:181]
	v_pk_mul_f32 v[150:151], v[114:115], v[168:169] op_sel_hi:[1,0]
	v_pk_fma_f32 v[150:151], v[0:1], v[150:151], v[8:9]
	v_pk_mul_f32 v[152:153], v[116:117], v[168:169] op_sel_hi:[1,0]
	v_pk_fma_f32 v[152:153], v[2:3], v[152:153], v[10:11]
	v_cvt_pk_bf16_f32 v190, v150, v151
	v_cvt_pk_bf16_f32 v191, v152, v153
	v_lshlrev_b32_e32 v154, 16, v190
	v_and_b32_e32 v155, 0xffff0000, v190
	v_pk_add_f32 v[150:151], v[150:151], v[154:155] neg_lo:[0,1] neg_hi:[0,1]
	v_cvt_pk_bf16_f32 v198, v150, v151
	v_lshlrev_b32_e32 v154, 16, v191
	v_and_b32_e32 v155, 0xffff0000, v191
	v_pk_add_f32 v[152:153], v[152:153], v[154:155] neg_lo:[0,1] neg_hi:[0,1]
	v_cvt_pk_bf16_f32 v199, v152, v153
	v_pk_mul_f32 v[150:151], v[118:119], v[168:169] op_sel_hi:[1,0]
	v_pk_fma_f32 v[150:151], v[4:5], v[150:151], v[12:13]
; __device__ __forceinline__ unsigned pk2(float lo, float hi) { return pg8::cvt_pk_bf16(lo, hi); }
; __device__ __forceinline__ float bflo(unsigned u) { return __uint_as_float(u << 16); }
; __device__ __forceinline__ float bfhi(unsigned u) { return __uint_as_float(u & 0xffff0000u); }
; __device__ __forceinline__ void ln_panel(int pm, const float* resf, const bf16* rlo, const bf16* dlt, float* xo, const float* gam, const float* bet, bf16* xb, bf16* wlo, bool fin, float alpha) {
;     ...
;         for (int j = 0; j < 4; ++j) { f32x4 x; const u32x2 d = *(const u32x2*)(dlt + prow + 256 * j);
;             if (resf) x = *(const f32x4*)(resf + grow + 256 * j);
;             else { const u32x2 h = *(const u32x2*)(xb + grow + 256 * j), l = *(const u32x2*)(rlo + prow + 256 * j);
;                    x = (f32x4){bflo(h.x) + bflo(l.x), bfhi(h.x) + bfhi(l.x), bflo(h.y) + bflo(l.y), bfhi(h.y) + bfhi(l.y)}; }
;             v[j] = (f32x4){x.x * alpha + bflo(d.x), x.y * alpha + bfhi(d.x), x.z * alpha + bflo(d.y), x.w * alpha + bfhi(d.y)}; s += (v[j].x + v[j].y) + (v[j].z + v[j].w); }
;         const float mean = wave_sum(s) * (1.f / DM); float s2 = 0.f;
; #pragma unroll
;         for (int j = 0; j < 4; ++j) { v[j] = v[j] - mean; s2 += (v[j].x * v[j].x + v[j].y * v[j].y) + (v[j].z * v[j].z + v[j].w * v[j].w); }
;         const float rstd = 1.f / sqrtf(wave_sum(s2) * (1.f / DM) + LN_EPS);
;     ...
;         for (int j = 0; j < 4; ++j) { const f32x4 o = v[j] * rstd * gv[j] + bv[j];
;             if (fin) *(f32x4*)(xo + grow + 256 * j) = o;
;             else { u32x2 w; w.x = pk2(o.x, o.y); w.y = pk2(o.z, o.w); *(u32x2*)(xb + grow + 256 * j) = w;
;                    u32x2 q; q.x = pk2(o.x - bflo(w.x), o.y - bfhi(w.x)); q.y = pk2(o.z - bflo(w.y), o.w - bfhi(w.y)); *(u32x2*)(wlo + prow + 256 * j) = q; } }
	v_pk_mul_f32 v[152:153], v[120:121], v[168:169] op_sel_hi:[1,0]
	v_pk_fma_f32 v[152:153], v[6:7], v[152:153], v[14:15]
	v_cvt_pk_bf16_f32 v192, v150, v151
	v_cvt_pk_bf16_f32 v193, v152, v153
	v_lshlrev_b32_e32 v154, 16, v192
	v_and_b32_e32 v155, 0xffff0000, v192
	v_pk_add_f32 v[150:151], v[150:151], v[154:155] neg_lo:[0,1] neg_hi:[0,1]
	v_cvt_pk_bf16_f32 v200, v150, v151
	v_lshlrev_b32_e32 v154, 16, v193
	v_and_b32_e32 v155, 0xffff0000, v193
	v_pk_add_f32 v[152:153], v[152:153], v[154:155] neg_lo:[0,1] neg_hi:[0,1]
	v_cvt_pk_bf16_f32 v201, v152, v153
	v_pk_mul_f32 v[150:151], v[122:123], v[168:169] op_sel_hi:[1,0]
	v_pk_fma_f32 v[150:151], v[16:17], v[150:151], v[24:25]
	v_pk_mul_f32 v[152:153], v[124:125], v[168:169] op_sel_hi:[1,0]
	v_pk_fma_f32 v[152:153], v[18:19], v[152:153], v[26:27]
	v_cvt_pk_bf16_f32 v194, v150, v151
	v_cvt_pk_bf16_f32 v195, v152, v153
	v_lshlrev_b32_e32 v154, 16, v194
	v_and_b32_e32 v155, 0xffff0000, v194
	v_pk_add_f32 v[150:151], v[150:151], v[154:155] neg_lo:[0,1] neg_hi:[0,1]
	v_cvt_pk_bf16_f32 v202, v150, v151
	v_lshlrev_b32_e32 v154, 16, v195
	v_and_b32_e32 v155, 0xffff0000, v195
	v_pk_add_f32 v[152:153], v[152:153], v[154:155] neg_lo:[0,1] neg_hi:[0,1]
	v_cvt_pk_bf16_f32 v203, v152, v153
	v_pk_mul_f32 v[150:151], v[126:127], v[168:169] op_sel_hi:[1,0]
	v_pk_fma_f32 v[150:151], v[20:21], v[150:151], v[28:29]
	v_pk_mul_f32 v[152:153], v[128:129], v[168:169] op_sel_hi:[1,0]
	v_pk_fma_f32 v[152:153], v[22:23], v[152:153], v[30:31]
	v_cvt_pk_bf16_f32 v196, v150, v151
	v_cvt_pk_bf16_f32 v197, v152, v153
	v_lshlrev_b32_e32 v154, 16, v196
	v_and_b32_e32 v155, 0xffff0000, v196
	v_pk_add_f32 v[150:151], v[150:151], v[154:155] neg_lo:[0,1] neg_hi:[0,1]
	v_cvt_pk_bf16_f32 v204, v150, v151
	v_lshlrev_b32_e32 v154, 16, v197
	v_and_b32_e32 v155, 0xffff0000, v197
	v_pk_add_f32 v[152:153], v[152:153], v[154:155] neg_lo:[0,1] neg_hi:[0,1]
	v_cvt_pk_bf16_f32 v205, v152, v153
	global_store_dwordx2 v[184:185], v[190:191], off offset:0
	global_store_dwordx2 v[184:185], v[192:193], off offset:512
	global_store_dwordx2 v[184:185], v[194:195], off offset:1024
	global_store_dwordx2 v[184:185], v[196:197], off offset:1536
	global_store_dwordx2 v[186:187], v[198:199], off offset:0
	global_store_dwordx2 v[186:187], v[200:201], off offset:512
	global_store_dwordx2 v[186:187], v[202:203], off offset:1024
	global_store_dwordx2 v[186:187], v[204:205], off offset:1536
	s_add_i32 s0, s98, 2
	s_min_u32 s0, s0, 31
	s_lshl_b32 s0, s0, 11
	s_mov_b32 s1, 0
	v_lshl_add_u64 v[184:185], s[0:1], 0, v[178:179]
	v_lshl_add_u64 v[186:187], s[0:1], 1, v[182:183]
	global_load_dwordx2 v[82:83], v[184:185], off offset:-1024 nt
	global_load_dwordx2 v[84:85], v[184:185], off offset:-512 nt
	global_load_dwordx2 v[86:87], v[184:185], off offset:0 nt
	global_load_dwordx2 v[88:89], v[184:185], off offset:512 nt
	global_load_dwordx4 v[66:69], v[186:187], off offset:0 nt
	global_load_dwordx4 v[70:73], v[186:187], off offset:1024 nt
	global_load_dwordx4 v[74:77], v[186:187], off offset:2048 nt
	global_load_dwordx4 v[78:81], v[186:187], off offset:3072 nt
	s_waitcnt vmcnt(16)
	v_lshlrev_b32_e32 v152, 16, v106
	v_and_b32_e32 v153, 0xffff0000, v106
	v_pk_fma_f32 v[114:115], v[90:91], v[164:165], v[152:153]
	v_lshlrev_b32_e32 v152, 16, v107
	v_and_b32_e32 v153, 0xffff0000, v107
	v_pk_fma_f32 v[116:117], v[92:93], v[164:165], v[152:153]
	v_lshlrev_b32_e32 v152, 16, v108
	v_and_b32_e32 v153, 0xffff0000, v108
	v_pk_fma_f32 v[118:119], v[94:95], v[164:165], v[152:153]
	v_lshlrev_b32_e32 v152, 16, v109
	v_and_b32_e32 v153, 0xffff0000, v109
	v_pk_fma_f32 v[120:121], v[96:97], v[164:165], v[152:153]
	v_lshlrev_b32_e32 v152, 16, v110
	v_and_b32_e32 v153, 0xffff0000, v110
	v_pk_fma_f32 v[122:123], v[98:99], v[164:165], v[152:153]
	v_lshlrev_b32_e32 v152, 16, v111
	v_and_b32_e32 v153, 0xffff0000, v111
	v_pk_fma_f32 v[124:125], v[100:101], v[164:165], v[152:153]
	v_lshlrev_b32_e32 v152, 16, v112
	v_and_b32_e32 v153, 0xffff0000, v112
	v_pk_fma_f32 v[126:127], v[102:103], v[164:165], v[152:153]
	v_lshlrev_b32_e32 v152, 16, v113
	v_and_b32_e32 v153, 0xffff0000, v113
	v_pk_fma_f32 v[128:129], v[104:105], v[164:165], v[152:153]
	v_pk_add_f32 v[154:155], v[114:115], v[116:117]
	v_pk_add_f32 v[156:157], v[118:119], v[120:121]
	v_pk_add_f32 v[154:155], v[154:155], v[156:157]
	v_pk_add_f32 v[156:157], v[122:123], v[124:125]
	v_pk_add_f32 v[154:155], v[154:155], v[156:157]
	v_pk_add_f32 v[156:157], v[126:127], v[128:129]
	v_pk_add_f32 v[154:155], v[154:155], v[156:157]
	v_add_f32_e32 v154, v154, v155
	s_nop 1
	v_add_f32_dpp v160, v154, v154 quad_perm:[1,0,3,2] row_mask:0xf bank_mask:0xf
	s_nop 1
	v_add_f32_dpp v160, v160, v160 quad_perm:[2,3,0,1] row_mask:0xf bank_mask:0xf
	s_nop 1
	v_add_f32_dpp v160, v160, v160 row_half_mirror row_mask:0xf bank_mask:0xf
	s_nop 1
	v_add_f32_dpp v160, v160, v160 row_mirror row_mask:0xf bank_mask:0xf
	s_nop 1
	v_add_f32_dpp v160, v160, v160 row_bcast:15 row_mask:0xa bank_mask:0xf
	s_nop 1
	v_add_f32_dpp v160, v160, v160 row_bcast:31 row_mask:0xc bank_mask:0xf
	s_nop 1
	v_readlane_b32 s0, v160, 63
	s_nop 2
	v_mov_b32_e32 v170, s0
	v_mul_f32_e32 v156, 0xba800000, v170
	v_mul_f32_e32 v157, 0xba800000, v170
	v_pk_add_f32 v[114:115], v[114:115], v[156:157]
	v_pk_add_f32 v[116:117], v[116:117], v[156:157]
	v_pk_add_f32 v[118:119], v[118:119], v[156:157]
	v_pk_add_f32 v[120:121], v[120:121], v[156:157]
	v_pk_add_f32 v[122:123], v[122:123], v[156:157]
	v_pk_add_f32 v[124:125], v[124:125], v[156:157]
	v_pk_add_f32 v[126:127], v[126:127], v[156:157]
	v_pk_add_f32 v[128:129], v[128:129], v[156:157]
	v_pk_mul_f32 v[154:155], v[114:115], v[114:115]
; __device__ __forceinline__ unsigned pk2(float lo, float hi) { return pg8::cvt_pk_bf16(lo, hi); }
; __device__ __forceinline__ float bflo(unsigned u) { return __uint_as_float(u << 16); }
; __device__ __forceinline__ float bfhi(unsigned u) { return __uint_as_float(u & 0xffff0000u); }
; __device__ __forceinline__ void ln_panel(int pm, const float* resf, const bf16* rlo, const bf16* dlt, float* xo, const float* gam, const float* bet, bf16* xb, bf16* wlo, bool fin, float alpha) {
;     ...
;         for (int j = 0; j < 4; ++j) { f32x4 x; const u32x2 d = *(const u32x2*)(dlt + prow + 256 * j);
;             if (resf) x = *(const f32x4*)(resf + grow + 256 * j);
;             else { const u32x2 h = *(const u32x2*)(xb + grow + 256 * j), l = *(const u32x2*)(rlo + prow + 256 * j);
;                    x = (f32x4){bflo(h.x) + bflo(l.x), bfhi(h.x) + bfhi(l.x), bflo(h.y) + bflo(l.y), bfhi(h.y) + bfhi(l.y)}; }
;     ...
;         for (int j = 0; j < 4; ++j) { v[j] = v[j] - mean; s2 += (v[j].x * v[j].x + v[j].y * v[j].y) + (v[j].z * v[j].z + v[j].w * v[j].w); }
;         const float rstd = 1.f / sqrtf(wave_sum(s2) * (1.f / DM) + LN_EPS);
; #pragma unroll
;         for (int j = 0; j < 4; ++j) { const f32x4 o = v[j] * rstd * gv[j] + bv[j];
;             if (fin) *(f32x4*)(xo + grow + 256 * j) = o;
;             else { u32x2 w; w.x = pk2(o.x, o.y); w.y = pk2(o.z, o.w); *(u32x2*)(xb + grow + 256 * j) = w;
;                    u32x2 q; q.x = pk2(o.x - bflo(w.x), o.y - bfhi(w.x)); q.y = pk2(o.z - bflo(w.y), o.w - bfhi(w.y)); *(u32x2*)(wlo + prow + 256 * j) = q; } }
	v_pk_fma_f32 v[154:155], v[116:117], v[116:117], v[154:155]
	v_pk_fma_f32 v[154:155], v[118:119], v[118:119], v[154:155]
	v_pk_fma_f32 v[154:155], v[120:121], v[120:121], v[154:155]
	v_pk_fma_f32 v[154:155], v[122:123], v[122:123], v[154:155]
	v_pk_fma_f32 v[154:155], v[124:125], v[124:125], v[154:155]
	v_pk_fma_f32 v[154:155], v[126:127], v[126:127], v[154:155]
	v_pk_fma_f32 v[154:155], v[128:129], v[128:129], v[154:155]
	v_add_f32_e32 v154, v154, v155
	s_nop 1
	v_add_f32_dpp v160, v154, v154 quad_perm:[1,0,3,2] row_mask:0xf bank_mask:0xf
	s_nop 1
	v_add_f32_dpp v160, v160, v160 quad_perm:[2,3,0,1] row_mask:0xf bank_mask:0xf
	s_nop 1
	v_add_f32_dpp v160, v160, v160 row_half_mirror row_mask:0xf bank_mask:0xf
	s_nop 1
	v_add_f32_dpp v160, v160, v160 row_mirror row_mask:0xf bank_mask:0xf
	s_nop 1
	v_add_f32_dpp v160, v160, v160 row_bcast:15 row_mask:0xa bank_mask:0xf
	s_nop 1
	v_add_f32_dpp v160, v160, v160 row_bcast:31 row_mask:0xc bank_mask:0xf
	s_nop 1
	v_readlane_b32 s0, v160, 63
	s_nop 2
	v_mov_b32_e32 v170, s0
	v_fmamk_f32 v154, v170, 0x3a800000, v166
	s_mov_b32 s0, 0xf800000
	v_mul_f32_e32 v155, 0x4f800000, v154
	v_cmp_gt_f32_e32 vcc, s0, v154
	s_nop 1
	v_cndmask_b32_e32 v154, v154, v155, vcc
	v_sqrt_f32_e32 v155, v154
	s_nop 0
	v_add_u32_e32 v156, -1, v155
	v_fma_f32 v157, -v156, v155, v154
	v_cmp_ge_f32_e64 s[0:1], 0, v157
	v_add_u32_e32 v157, 1, v155
	s_nop 0
	v_cndmask_b32_e64 v156, v155, v156, s[0:1]
	v_fma_f32 v155, -v157, v155, v154
	v_cmp_lt_f32_e64 s[0:1], 0, v155
	s_nop 1
	v_cndmask_b32_e64 v155, v156, v157, s[0:1]
	v_mul_f32_e32 v156, 0x37800000, v155
	v_cndmask_b32_e32 v155, v155, v156, vcc
	v_cmp_class_f32_e32 vcc, v154, v167
	s_nop 1
	v_cndmask_b32_e32 v154, v155, v154, vcc
	v_div_scale_f32 v155, s[0:1], v154, v154, 1.0
	v_rcp_f32_e32 v156, v155
	s_nop 0
	v_fma_f32 v157, -v155, v156, 1.0
	v_fmac_f32_e32 v156, v157, v156
	v_div_scale_f32 v157, vcc, 1.0, v154, 1.0
	v_mul_f32_e32 v158, v157, v156
	v_fma_f32 v159, -v155, v158, v157
	v_fmac_f32_e32 v158, v159, v156
	v_fma_f32 v155, -v155, v158, v157
	s_nop 0
	v_div_fmas_f32 v155, v155, v156, v158
	v_div_fixup_f32 v168, v155, v154, 1.0
	s_add_i32 s0, s98, 1
	s_lshl_b32 s0, s0, 11
	s_mov_b32 s1, 0
	v_lshl_add_u64 v[184:185], s[0:1], 0, v[172:173]
	v_lshl_add_u64 v[186:187], s[0:1], 0, v[180:181]
	v_pk_mul_f32 v[150:151], v[114:115], v[168:169] op_sel_hi:[1,0]
	v_pk_fma_f32 v[150:151], v[0:1], v[150:151], v[8:9]
	v_pk_mul_f32 v[152:153], v[116:117], v[168:169] op_sel_hi:[1,0]
	v_pk_fma_f32 v[152:153], v[2:3], v[152:153], v[10:11]
	v_cvt_pk_bf16_f32 v190, v150, v151
	v_cvt_pk_bf16_f32 v191, v152, v153
	v_lshlrev_b32_e32 v154, 16, v190
	v_and_b32_e32 v155, 0xffff0000, v190
	v_pk_add_f32 v[150:151], v[150:151], v[154:155] neg_lo:[0,1] neg_hi:[0,1]
	v_cvt_pk_bf16_f32 v198, v150, v151
	v_lshlrev_b32_e32 v154, 16, v191
	v_and_b32_e32 v155, 0xffff0000, v191
	v_pk_add_f32 v[152:153], v[152:153], v[154:155] neg_lo:[0,1] neg_hi:[0,1]
	v_cvt_pk_bf16_f32 v199, v152, v153
	v_pk_mul_f32 v[150:151], v[118:119], v[168:169] op_sel_hi:[1,0]
	v_pk_fma_f32 v[150:151], v[4:5], v[150:151], v[12:13]
	v_pk_mul_f32 v[152:153], v[120:121], v[168:169] op_sel_hi:[1,0]
	v_pk_fma_f32 v[152:153], v[6:7], v[152:153], v[14:15]
	v_cvt_pk_bf16_f32 v192, v150, v151
	v_cvt_pk_bf16_f32 v193, v152, v153
	v_lshlrev_b32_e32 v154, 16, v192
	v_and_b32_e32 v155, 0xffff0000, v192
	v_pk_add_f32 v[150:151], v[150:151], v[154:155] neg_lo:[0,1] neg_hi:[0,1]
	v_cvt_pk_bf16_f32 v200, v150, v151
	v_lshlrev_b32_e32 v154, 16, v193
	v_and_b32_e32 v155, 0xffff0000, v193
	v_pk_add_f32 v[152:153], v[152:153], v[154:155] neg_lo:[0,1] neg_hi:[0,1]
	v_cvt_pk_bf16_f32 v201, v152, v153
	v_pk_mul_f32 v[150:151], v[122:123], v[168:169] op_sel_hi:[1,0]
	v_pk_fma_f32 v[150:151], v[16:17], v[150:151], v[24:25]
	v_pk_mul_f32 v[152:153], v[124:125], v[168:169] op_sel_hi:[1,0]
	v_pk_fma_f32 v[152:153], v[18:19], v[152:153], v[26:27]
	v_cvt_pk_bf16_f32 v194, v150, v151
	v_cvt_pk_bf16_f32 v195, v152, v153
	v_lshlrev_b32_e32 v154, 16, v194
	v_and_b32_e32 v155, 0xffff0000, v194
	v_pk_add_f32 v[150:151], v[150:151], v[154:155] neg_lo:[0,1] neg_hi:[0,1]
	v_cvt_pk_bf16_f32 v202, v150, v151
	v_lshlrev_b32_e32 v154, 16, v195
	v_and_b32_e32 v155, 0xffff0000, v195
	v_pk_add_f32 v[152:153], v[152:153], v[154:155] neg_lo:[0,1] neg_hi:[0,1]
	v_cvt_pk_bf16_f32 v203, v152, v153
	v_pk_mul_f32 v[150:151], v[126:127], v[168:169] op_sel_hi:[1,0]
	v_pk_fma_f32 v[150:151], v[20:21], v[150:151], v[28:29]
	v_pk_mul_f32 v[152:153], v[128:129], v[168:169] op_sel_hi:[1,0]
	v_pk_fma_f32 v[152:153], v[22:23], v[152:153], v[30:31]
	v_cvt_pk_bf16_f32 v196, v150, v151
	v_cvt_pk_bf16_f32 v197, v152, v153
	v_lshlrev_b32_e32 v154, 16, v196
	v_and_b32_e32 v155, 0xffff0000, v196
	v_pk_add_f32 v[150:151], v[150:151], v[154:155] neg_lo:[0,1] neg_hi:[0,1]
	v_cvt_pk_bf16_f32 v204, v150, v151
	v_lshlrev_b32_e32 v154, 16, v197
	v_and_b32_e32 v155, 0xffff0000, v197
	v_pk_add_f32 v[152:153], v[152:153], v[154:155] neg_lo:[0,1] neg_hi:[0,1]
	v_cvt_pk_bf16_f32 v205, v152, v153
	global_store_dwordx2 v[184:185], v[190:191], off offset:0
	global_store_dwordx2 v[184:185], v[192:193], off offset:512
	global_store_dwordx2 v[184:185], v[194:195], off offset:1024
	global_store_dwordx2 v[184:185], v[196:197], off offset:1536
	global_store_dwordx2 v[186:187], v[198:199], off offset:0
	global_store_dwordx2 v[186:187], v[200:201], off offset:512
	global_store_dwordx2 v[186:187], v[202:203], off offset:1024
	global_store_dwordx2 v[186:187], v[204:205], off offset:1536
	s_add_i32 s0, s98, 3
	s_min_u32 s0, s0, 31
	s_lshl_b32 s0, s0, 11
	s_mov_b32 s1, 0
	v_lshl_add_u64 v[184:185], s[0:1], 0, v[178:179]
	v_lshl_add_u64 v[186:187], s[0:1], 1, v[182:183]
	global_load_dwordx2 v[106:107], v[184:185], off offset:-1024 nt
	global_load_dwordx2 v[108:109], v[184:185], off offset:-512 nt
	global_load_dwordx2 v[110:111], v[184:185], off offset:0 nt
	global_load_dwordx2 v[112:113], v[184:185], off offset:512 nt
	global_load_dwordx4 v[90:93], v[186:187], off offset:0 nt
	global_load_dwordx4 v[94:97], v[186:187], off offset:1024 nt
	global_load_dwordx4 v[98:101], v[186:187], off offset:2048 nt
	global_load_dwordx4 v[102:105], v[186:187], off offset:3072 nt
	s_add_i32 s98, s98, 2
	s_cmp_lt_u32 s98, 32
	s_cbranch_scc1 .Lmy_ln1r_loop
	s_waitcnt vmcnt(0)
	s_branch .LBB0_557

; __device__ __forceinline__ void ln_panel(int pm, const float* resf, const bf16* rlo, const bf16* dlt, float* xo, const float* gam, const float* bet, bf16* xb, bf16* wlo, bool fin, float alpha) {
;     ...
;     for (int r = wave * 32; r < wave * 32 + 32; ++r) {
;         const size_t grow = (size_t)(pm * 256 + r) * DM + 4 * lane, prow = (size_t)r * DM + 4 * lane;
;         f32x4 v[4]; float s = 0.f;
; #pragma unroll
;         for (int j = 0; j < 4; ++j) { f32x4 x; const u32x2 d = *(const u32x2*)(dlt + prow + 256 * j);
;             if (resf) x = *(const f32x4*)(resf + grow + 256 * j);
;             else { const u32x2 h = *(const u32x2*)(xb + grow + 256 * j), l = *(const u32x2*)(rlo + prow + 256 * j);
.Lmy_ln2h_start:
	s_mov_b32 s98, 0
	s_add_i32 s0, s98, 0
	s_min_u32 s0, s0, 31
	s_lshl_b32 s0, s0, 11
	s_mov_b32 s1, 0
	v_lshl_add_u64 v[184:185], s[0:1], 0, v[178:179]
	v_lshl_add_u64 v[186:187], s[0:1], 0, v[172:173]
	v_lshl_add_u64 v[188:189], s[0:1], 0, v[176:177]
	global_load_dwordx2 v[82:83], v[184:185], off offset:-1024 nt
	global_load_dwordx2 v[84:85], v[184:185], off offset:-512 nt
	global_load_dwordx2 v[86:87], v[184:185], off offset:0 nt
	global_load_dwordx2 v[88:89], v[184:185], off offset:512 nt
	global_load_dwordx2 v[66:67], v[186:187], off offset:-1024
	global_load_dwordx2 v[68:69], v[186:187], off offset:-512
	global_load_dwordx2 v[70:71], v[186:187], off offset:0
	global_load_dwordx2 v[72:73], v[186:187], off offset:512
	global_load_dwordx2 v[74:75], v[188:189], off offset:-1024 nt
	global_load_dwordx2 v[76:77], v[188:189], off offset:-512 nt
	global_load_dwordx2 v[78:79], v[188:189], off offset:0 nt
	global_load_dwordx2 v[80:81], v[188:189], off offset:512 nt
	s_add_i32 s0, s98, 1
	s_min_u32 s0, s0, 31
	s_lshl_b32 s0, s0, 11
	s_mov_b32 s1, 0
	v_lshl_add_u64 v[184:185], s[0:1], 0, v[178:179]
	v_lshl_add_u64 v[186:187], s[0:1], 0, v[172:173]
	v_lshl_add_u64 v[188:189], s[0:1], 0, v[176:177]
	global_load_dwordx2 v[106:107], v[184:185], off offset:-1024 nt
	global_load_dwordx2 v[108:109], v[184:185], off offset:-512 nt
	global_load_dwordx2 v[110:111], v[184:185], off offset:0 nt
	global_load_dwordx2 v[112:113], v[184:185], off offset:512 nt
	global_load_dwordx2 v[90:91], v[186:187], off offset:-1024
	global_load_dwordx2 v[92:93], v[186:187], off offset:-512
	global_load_dwordx2 v[94:95], v[186:187], off offset:0
	global_load_dwordx2 v[96:97], v[186:187], off offset:512
	global_load_dwordx2 v[98:99], v[188:189], off offset:-1024 nt
	global_load_dwordx2 v[100:101], v[188:189], off offset:-512 nt
	global_load_dwordx2 v[102:103], v[188:189], off offset:0 nt
	global_load_dwordx2 v[104:105], v[188:189], off offset:512 nt
	s_waitcnt vmcnt(12)
	s_branch .Lmy_ln2h_entry

; __device__ __forceinline__ float bflo(unsigned u) { return __uint_as_float(u << 16); }
; __device__ __forceinline__ float bfhi(unsigned u) { return __uint_as_float(u & 0xffff0000u); }
; __device__ __forceinline__ void ln_panel(int pm, const float* resf, const bf16* rlo, const bf16* dlt, float* xo, const float* gam, const float* bet, bf16* xb, bf16* wlo, bool fin, float alpha) {
;     ...
;         for (int j = 0; j < 4; ++j) { f32x4 x; const u32x2 d = *(const u32x2*)(dlt + prow + 256 * j);
;             if (resf) x = *(const f32x4*)(resf + grow + 256 * j);
;             else { const u32x2 h = *(const u32x2*)(xb + grow + 256 * j), l = *(const u32x2*)(rlo + prow + 256 * j);
;                    x = (f32x4){bflo(h.x) + bflo(l.x), bfhi(h.x) + bfhi(l.x), bflo(h.y) + bflo(l.y), bfhi(h.y) + bfhi(l.y)}; }
;             v[j] = (f32x4){x.x * alpha + bflo(d.x), x.y * alpha + bfhi(d.x), x.z * alpha + bflo(d.y), x.w * alpha + bfhi(d.y)}; s += (v[j].x + v[j].y) + (v[j].z + v[j].w); }
;         const float mean = wave_sum(s) * (1.f / DM); float s2 = 0.f;
; #pragma unroll
;         for (int j = 0; j < 4; ++j) { v[j] = v[j] - mean; s2 += (v[j].x * v[j].x + v[j].y * v[j].y) + (v[j].z * v[j].z + v[j].w * v[j].w); }
;         const float rstd = 1.f / sqrtf(wave_sum(s2) * (1.f / DM) + LN_EPS);
.Lmy_ln2h_entry:
	v_lshlrev_b32_e32 v150, 16, v66
	v_and_b32_e32 v151, 0xffff0000, v66
	v_lshlrev_b32_e32 v152, 16, v74
	v_and_b32_e32 v153, 0xffff0000, v74
	v_pk_add_f32 v[150:151], v[150:151], v[152:153]
	v_lshlrev_b32_e32 v152, 16, v82
	v_and_b32_e32 v153, 0xffff0000, v82
	v_pk_fma_f32 v[114:115], v[150:151], v[164:165], v[152:153]
	v_lshlrev_b32_e32 v150, 16, v67
	v_and_b32_e32 v151, 0xffff0000, v67
	v_lshlrev_b32_e32 v152, 16, v75
	v_and_b32_e32 v153, 0xffff0000, v75
	v_pk_add_f32 v[150:151], v[150:151], v[152:153]
	v_lshlrev_b32_e32 v152, 16, v83
	v_and_b32_e32 v153, 0xffff0000, v83
	v_pk_fma_f32 v[116:117], v[150:151], v[164:165], v[152:153]
	v_lshlrev_b32_e32 v150, 16, v68
	v_and_b32_e32 v151, 0xffff0000, v68
	v_lshlrev_b32_e32 v152, 16, v76
	v_and_b32_e32 v153, 0xffff0000, v76
	v_pk_add_f32 v[150:151], v[150:151], v[152:153]
	v_lshlrev_b32_e32 v152, 16, v84
	v_and_b32_e32 v153, 0xffff0000, v84
	v_pk_fma_f32 v[118:119], v[150:151], v[164:165], v[152:153]
	v_lshlrev_b32_e32 v150, 16, v69
	v_and_b32_e32 v151, 0xffff0000, v69
	v_lshlrev_b32_e32 v152, 16, v77
	v_and_b32_e32 v153, 0xffff0000, v77
	v_pk_add_f32 v[150:151], v[150:151], v[152:153]
	v_lshlrev_b32_e32 v152, 16, v85
	v_and_b32_e32 v153, 0xffff0000, v85
	v_pk_fma_f32 v[120:121], v[150:151], v[164:165], v[152:153]
	v_lshlrev_b32_e32 v150, 16, v70
	v_and_b32_e32 v151, 0xffff0000, v70
	v_lshlrev_b32_e32 v152, 16, v78
	v_and_b32_e32 v153, 0xffff0000, v78
	v_pk_add_f32 v[150:151], v[150:151], v[152:153]
	v_lshlrev_b32_e32 v152, 16, v86
	v_and_b32_e32 v153, 0xffff0000, v86
	v_pk_fma_f32 v[122:123], v[150:151], v[164:165], v[152:153]
	v_lshlrev_b32_e32 v150, 16, v71
	v_and_b32_e32 v151, 0xffff0000, v71
	v_lshlrev_b32_e32 v152, 16, v79
	v_and_b32_e32 v153, 0xffff0000, v79
	v_pk_add_f32 v[150:151], v[150:151], v[152:153]
	v_lshlrev_b32_e32 v152, 16, v87
	v_and_b32_e32 v153, 0xffff0000, v87
	v_pk_fma_f32 v[124:125], v[150:151], v[164:165], v[152:153]
	v_lshlrev_b32_e32 v150, 16, v72
	v_and_b32_e32 v151, 0xffff0000, v72
	v_lshlrev_b32_e32 v152, 16, v80
	v_and_b32_e32 v153, 0xffff0000, v80
	v_pk_add_f32 v[150:151], v[150:151], v[152:153]
	v_lshlrev_b32_e32 v152, 16, v88
	v_and_b32_e32 v153, 0xffff0000, v88
	v_pk_fma_f32 v[126:127], v[150:151], v[164:165], v[152:153]
	v_lshlrev_b32_e32 v150, 16, v73
	v_and_b32_e32 v151, 0xffff0000, v73
	v_lshlrev_b32_e32 v152, 16, v81
	v_and_b32_e32 v153, 0xffff0000, v81
	v_pk_add_f32 v[150:151], v[150:151], v[152:153]
	v_lshlrev_b32_e32 v152, 16, v89
	v_and_b32_e32 v153, 0xffff0000, v89
	v_pk_fma_f32 v[128:129], v[150:151], v[164:165], v[152:153]
	v_pk_add_f32 v[154:155], v[114:115], v[116:117]
	v_pk_add_f32 v[156:157], v[118:119], v[120:121]
	v_pk_add_f32 v[154:155], v[154:155], v[156:157]
	v_pk_add_f32 v[156:157], v[122:123], v[124:125]
	v_pk_add_f32 v[154:155], v[154:155], v[156:157]
	v_pk_add_f32 v[156:157], v[126:127], v[128:129]
	v_pk_add_f32 v[154:155], v[154:155], v[156:157]
	v_add_f32_e32 v154, v154, v155
	s_nop 1
	v_add_f32_dpp v160, v154, v154 quad_perm:[1,0,3,2] row_mask:0xf bank_mask:0xf
	s_nop 1
	v_add_f32_dpp v160, v160, v160 quad_perm:[2,3,0,1] row_mask:0xf bank_mask:0xf
	s_nop 1
	v_add_f32_dpp v160, v160, v160 row_half_mirror row_mask:0xf bank_mask:0xf
	s_nop 1
	v_add_f32_dpp v160, v160, v160 row_mirror row_mask:0xf bank_mask:0xf
	s_nop 1
	v_add_f32_dpp v160, v160, v160 row_bcast:15 row_mask:0xa bank_mask:0xf
	s_nop 1
	v_add_f32_dpp v160, v160, v160 row_bcast:31 row_mask:0xc bank_mask:0xf
	s_nop 1
	v_readlane_b32 s0, v160, 63
	s_nop 2
	v_mov_b32_e32 v170, s0
	v_mul_f32_e32 v156, 0xba800000, v170
	v_mul_f32_e32 v157, 0xba800000, v170
	v_pk_add_f32 v[114:115], v[114:115], v[156:157]
	v_pk_add_f32 v[116:117], v[116:117], v[156:157]
	v_pk_add_f32 v[118:119], v[118:119], v[156:157]
	v_pk_add_f32 v[120:121], v[120:121], v[156:157]
	v_pk_add_f32 v[122:123], v[122:123], v[156:157]
	v_pk_add_f32 v[124:125], v[124:125], v[156:157]
	v_pk_add_f32 v[126:127], v[126:127], v[156:157]
	v_pk_add_f32 v[128:129], v[128:129], v[156:157]
	v_pk_mul_f32 v[154:155], v[114:115], v[114:115]
	v_pk_fma_f32 v[154:155], v[116:117], v[116:117], v[154:155]
	v_pk_fma_f32 v[154:155], v[118:119], v[118:119], v[154:155]
	v_pk_fma_f32 v[154:155], v[120:121], v[120:121], v[154:155]
	v_pk_fma_f32 v[154:155], v[122:123], v[122:123], v[154:155]
	v_pk_fma_f32 v[154:155], v[124:125], v[124:125], v[154:155]
	v_pk_fma_f32 v[154:155], v[126:127], v[126:127], v[154:155]
	v_pk_fma_f32 v[154:155], v[128:129], v[128:129], v[154:155]
	v_add_f32_e32 v154, v154, v155
	s_nop 1
	v_add_f32_dpp v160, v154, v154 quad_perm:[1,0,3,2] row_mask:0xf bank_mask:0xf
	s_nop 1
	v_add_f32_dpp v160, v160, v160 quad_perm:[2,3,0,1] row_mask:0xf bank_mask:0xf
	s_nop 1
	v_add_f32_dpp v160, v160, v160 row_half_mirror row_mask:0xf bank_mask:0xf
	s_nop 1
	v_add_f32_dpp v160, v160, v160 row_mirror row_mask:0xf bank_mask:0xf
	s_nop 1
	v_add_f32_dpp v160, v160, v160 row_bcast:15 row_mask:0xa bank_mask:0xf
	s_nop 1
	v_add_f32_dpp v160, v160, v160 row_bcast:31 row_mask:0xc bank_mask:0xf
	s_nop 1
	v_readlane_b32 s0, v160, 63
	s_nop 2
	v_mov_b32_e32 v170, s0
	v_fmamk_f32 v154, v170, 0x3a800000, v166
	s_mov_b32 s0, 0xf800000
	v_mul_f32_e32 v155, 0x4f800000, v154
	v_cmp_gt_f32_e32 vcc, s0, v154
	s_nop 1
	v_cndmask_b32_e32 v154, v154, v155, vcc
	v_sqrt_f32_e32 v155, v154
	s_nop 0
	v_add_u32_e32 v156, -1, v155
	v_fma_f32 v157, -v156, v155, v154
	v_cmp_ge_f32_e64 s[0:1], 0, v157
	v_add_u32_e32 v157, 1, v155
	s_nop 0
	v_cndmask_b32_e64 v156, v155, v156, s[0:1]
	v_fma_f32 v155, -v157, v155, v154
	v_cmp_lt_f32_e64 s[0:1], 0, v155
	s_nop 1
	v_cndmask_b32_e64 v155, v156, v157, s[0:1]
	v_mul_f32_e32 v156, 0x37800000, v155
; __device__ __forceinline__ unsigned pk2(float lo, float hi) { return pg8::cvt_pk_bf16(lo, hi); }
; __device__ __forceinline__ float bflo(unsigned u) { return __uint_as_float(u << 16); }
; __device__ __forceinline__ float bfhi(unsigned u) { return __uint_as_float(u & 0xffff0000u); }
; __device__ __forceinline__ void ln_panel(int pm, const float* resf, const bf16* rlo, const bf16* dlt, float* xo, const float* gam, const float* bet, bf16* xb, bf16* wlo, bool fin, float alpha) {
;     ...
;         for (int j = 0; j < 4; ++j) { f32x4 x; const u32x2 d = *(const u32x2*)(dlt + prow + 256 * j);
;             if (resf) x = *(const f32x4*)(resf + grow + 256 * j);
;             else { const u32x2 h = *(const u32x2*)(xb + grow + 256 * j), l = *(const u32x2*)(rlo + prow + 256 * j);
;     ...
;         const float rstd = 1.f / sqrtf(wave_sum(s2) * (1.f / DM) + LN_EPS);
; #pragma unroll
;         for (int j = 0; j < 4; ++j) { const f32x4 o = v[j] * rstd * gv[j] + bv[j];
;             if (fin) *(f32x4*)(xo + grow + 256 * j) = o;
;             else { u32x2 w; w.x = pk2(o.x, o.y); w.y = pk2(o.z, o.w); *(u32x2*)(xb + grow + 256 * j) = w;
;                    u32x2 q; q.x = pk2(o.x - bflo(w.x), o.y - bfhi(w.x)); q.y = pk2(o.z - bflo(w.y), o.w - bfhi(w.y)); *(u32x2*)(wlo + prow + 256 * j) = q; } }
	v_cndmask_b32_e32 v155, v155, v156, vcc
	v_cmp_class_f32_e32 vcc, v154, v167
	s_nop 1
	v_cndmask_b32_e32 v154, v155, v154, vcc
	v_div_scale_f32 v155, s[0:1], v154, v154, 1.0
	v_rcp_f32_e32 v156, v155
	s_nop 0
	v_fma_f32 v157, -v155, v156, 1.0
	v_fmac_f32_e32 v156, v157, v156
	v_div_scale_f32 v157, vcc, 1.0, v154, 1.0
	v_mul_f32_e32 v158, v157, v156
	v_fma_f32 v159, -v155, v158, v157
	v_fmac_f32_e32 v158, v159, v156
	v_fma_f32 v155, -v155, v158, v157
	s_nop 0
	v_div_fmas_f32 v155, v155, v156, v158
	v_div_fixup_f32 v168, v155, v154, 1.0
	s_add_i32 s0, s98, 0
	s_lshl_b32 s0, s0, 11
	s_mov_b32 s1, 0
	v_lshl_add_u64 v[184:185], s[0:1], 0, v[172:173]
	v_lshl_add_u64 v[186:187], s[0:1], 0, v[180:181]
	v_pk_mul_f32 v[150:151], v[114:115], v[168:169] op_sel_hi:[1,0]
	v_pk_fma_f32 v[150:151], v[0:1], v[150:151], v[8:9]
	v_pk_mul_f32 v[152:153], v[116:117], v[168:169] op_sel_hi:[1,0]
	v_pk_fma_f32 v[152:153], v[2:3], v[152:153], v[10:11]
	v_cvt_pk_bf16_f32 v190, v150, v151
	v_cvt_pk_bf16_f32 v191, v152, v153
	v_lshlrev_b32_e32 v154, 16, v190
	v_and_b32_e32 v155, 0xffff0000, v190
	v_pk_add_f32 v[150:151], v[150:151], v[154:155] neg_lo:[0,1] neg_hi:[0,1]
	v_cvt_pk_bf16_f32 v198, v150, v151
	v_lshlrev_b32_e32 v154, 16, v191
	v_and_b32_e32 v155, 0xffff0000, v191
	v_pk_add_f32 v[152:153], v[152:153], v[154:155] neg_lo:[0,1] neg_hi:[0,1]
	v_cvt_pk_bf16_f32 v199, v152, v153
	v_pk_mul_f32 v[150:151], v[118:119], v[168:169] op_sel_hi:[1,0]
	v_pk_fma_f32 v[150:151], v[4:5], v[150:151], v[12:13]
	v_pk_mul_f32 v[152:153], v[120:121], v[168:169] op_sel_hi:[1,0]
	v_pk_fma_f32 v[152:153], v[6:7], v[152:153], v[14:15]
	v_cvt_pk_bf16_f32 v192, v150, v151
	v_cvt_pk_bf16_f32 v193, v152, v153
	v_lshlrev_b32_e32 v154, 16, v192
	v_and_b32_e32 v155, 0xffff0000, v192
	v_pk_add_f32 v[150:151], v[150:151], v[154:155] neg_lo:[0,1] neg_hi:[0,1]
	v_cvt_pk_bf16_f32 v200, v150, v151
	v_lshlrev_b32_e32 v154, 16, v193
	v_and_b32_e32 v155, 0xffff0000, v193
	v_pk_add_f32 v[152:153], v[152:153], v[154:155] neg_lo:[0,1] neg_hi:[0,1]
	v_cvt_pk_bf16_f32 v201, v152, v153
	v_pk_mul_f32 v[150:151], v[122:123], v[168:169] op_sel_hi:[1,0]
	v_pk_fma_f32 v[150:151], v[16:17], v[150:151], v[24:25]
	v_pk_mul_f32 v[152:153], v[124:125], v[168:169] op_sel_hi:[1,0]
	v_pk_fma_f32 v[152:153], v[18:19], v[152:153], v[26:27]
	v_cvt_pk_bf16_f32 v194, v150, v151
	v_cvt_pk_bf16_f32 v195, v152, v153
	v_lshlrev_b32_e32 v154, 16, v194
	v_and_b32_e32 v155, 0xffff0000, v194
	v_pk_add_f32 v[150:151], v[150:151], v[154:155] neg_lo:[0,1] neg_hi:[0,1]
	v_cvt_pk_bf16_f32 v202, v150, v151
	v_lshlrev_b32_e32 v154, 16, v195
	v_and_b32_e32 v155, 0xffff0000, v195
	v_pk_add_f32 v[152:153], v[152:153], v[154:155] neg_lo:[0,1] neg_hi:[0,1]
	v_cvt_pk_bf16_f32 v203, v152, v153
	v_pk_mul_f32 v[150:151], v[126:127], v[168:169] op_sel_hi:[1,0]
	v_pk_fma_f32 v[150:151], v[20:21], v[150:151], v[28:29]
	v_pk_mul_f32 v[152:153], v[128:129], v[168:169] op_sel_hi:[1,0]
	v_pk_fma_f32 v[152:153], v[22:23], v[152:153], v[30:31]
	v_cvt_pk_bf16_f32 v196, v150, v151
	v_cvt_pk_bf16_f32 v197, v152, v153
	v_lshlrev_b32_e32 v154, 16, v196
	v_and_b32_e32 v155, 0xffff0000, v196
	v_pk_add_f32 v[150:151], v[150:151], v[154:155] neg_lo:[0,1] neg_hi:[0,1]
	v_cvt_pk_bf16_f32 v204, v150, v151
	v_lshlrev_b32_e32 v154, 16, v197
	v_and_b32_e32 v155, 0xffff0000, v197
	v_pk_add_f32 v[152:153], v[152:153], v[154:155] neg_lo:[0,1] neg_hi:[0,1]
	v_cvt_pk_bf16_f32 v205, v152, v153
	global_store_dwordx2 v[184:185], v[190:191], off offset:-1024
	global_store_dwordx2 v[184:185], v[192:193], off offset:-512
	global_store_dwordx2 v[184:185], v[194:195], off offset:0
	global_store_dwordx2 v[184:185], v[196:197], off offset:512
	global_store_dwordx2 v[186:187], v[198:199], off offset:0
	global_store_dwordx2 v[186:187], v[200:201], off offset:512
	global_store_dwordx2 v[186:187], v[202:203], off offset:1024
	global_store_dwordx2 v[186:187], v[204:205], off offset:1536
	s_add_i32 s0, s98, 2
	s_min_u32 s0, s0, 31
	s_lshl_b32 s0, s0, 11
	s_mov_b32 s1, 0
	v_lshl_add_u64 v[184:185], s[0:1], 0, v[178:179]
	v_lshl_add_u64 v[186:187], s[0:1], 0, v[172:173]
	v_lshl_add_u64 v[188:189], s[0:1], 0, v[176:177]
	global_load_dwordx2 v[82:83], v[184:185], off offset:-1024 nt
	global_load_dwordx2 v[84:85], v[184:185], off offset:-512 nt
	global_load_dwordx2 v[86:87], v[184:185], off offset:0 nt
	global_load_dwordx2 v[88:89], v[184:185], off offset:512 nt
	global_load_dwordx2 v[66:67], v[186:187], off offset:-1024
	global_load_dwordx2 v[68:69], v[186:187], off offset:-512
	global_load_dwordx2 v[70:71], v[186:187], off offset:0
	global_load_dwordx2 v[72:73], v[186:187], off offset:512
	global_load_dwordx2 v[74:75], v[188:189], off offset:-1024 nt
	global_load_dwordx2 v[76:77], v[188:189], off offset:-512 nt
	global_load_dwordx2 v[78:79], v[188:189], off offset:0 nt
	global_load_dwordx2 v[80:81], v[188:189], off offset:512 nt
	s_waitcnt vmcnt(20)
; __device__ __forceinline__ float bflo(unsigned u) { return __uint_as_float(u << 16); }
; __device__ __forceinline__ float bfhi(unsigned u) { return __uint_as_float(u & 0xffff0000u); }
; __device__ __forceinline__ void ln_panel(int pm, const float* resf, const bf16* rlo, const bf16* dlt, float* xo, const float* gam, const float* bet, bf16* xb, bf16* wlo, bool fin, float alpha) {
;     ...
;         for (int j = 0; j < 4; ++j) { f32x4 x; const u32x2 d = *(const u32x2*)(dlt + prow + 256 * j);
;             if (resf) x = *(const f32x4*)(resf + grow + 256 * j);
;             else { const u32x2 h = *(const u32x2*)(xb + grow + 256 * j), l = *(const u32x2*)(rlo + prow + 256 * j);
;                    x = (f32x4){bflo(h.x) + bflo(l.x), bfhi(h.x) + bfhi(l.x), bflo(h.y) + bflo(l.y), bfhi(h.y) + bfhi(l.y)}; }
;             v[j] = (f32x4){x.x * alpha + bflo(d.x), x.y * alpha + bfhi(d.x), x.z * alpha + bflo(d.y), x.w * alpha + bfhi(d.y)}; s += (v[j].x + v[j].y) + (v[j].z + v[j].w); }
;         const float mean = wave_sum(s) * (1.f / DM); float s2 = 0.f;
; #pragma unroll
;         for (int j = 0; j < 4; ++j) { v[j] = v[j] - mean; s2 += (v[j].x * v[j].x + v[j].y * v[j].y) + (v[j].z * v[j].z + v[j].w * v[j].w); }
;         const float rstd = 1.f / sqrtf(wave_sum(s2) * (1.f / DM) + LN_EPS);
	v_lshlrev_b32_e32 v150, 16, v90
	v_and_b32_e32 v151, 0xffff0000, v90
	v_lshlrev_b32_e32 v152, 16, v98
	v_and_b32_e32 v153, 0xffff0000, v98
	v_pk_add_f32 v[150:151], v[150:151], v[152:153]
	v_lshlrev_b32_e32 v152, 16, v106
	v_and_b32_e32 v153, 0xffff0000, v106
	v_pk_fma_f32 v[114:115], v[150:151], v[164:165], v[152:153]
	v_lshlrev_b32_e32 v150, 16, v91
	v_and_b32_e32 v151, 0xffff0000, v91
	v_lshlrev_b32_e32 v152, 16, v99
	v_and_b32_e32 v153, 0xffff0000, v99
	v_pk_add_f32 v[150:151], v[150:151], v[152:153]
	v_lshlrev_b32_e32 v152, 16, v107
	v_and_b32_e32 v153, 0xffff0000, v107
	v_pk_fma_f32 v[116:117], v[150:151], v[164:165], v[152:153]
	v_lshlrev_b32_e32 v150, 16, v92
	v_and_b32_e32 v151, 0xffff0000, v92
	v_lshlrev_b32_e32 v152, 16, v100
	v_and_b32_e32 v153, 0xffff0000, v100
	v_pk_add_f32 v[150:151], v[150:151], v[152:153]
	v_lshlrev_b32_e32 v152, 16, v108
	v_and_b32_e32 v153, 0xffff0000, v108
	v_pk_fma_f32 v[118:119], v[150:151], v[164:165], v[152:153]
	v_lshlrev_b32_e32 v150, 16, v93
	v_and_b32_e32 v151, 0xffff0000, v93
	v_lshlrev_b32_e32 v152, 16, v101
	v_and_b32_e32 v153, 0xffff0000, v101
	v_pk_add_f32 v[150:151], v[150:151], v[152:153]
	v_lshlrev_b32_e32 v152, 16, v109
	v_and_b32_e32 v153, 0xffff0000, v109
	v_pk_fma_f32 v[120:121], v[150:151], v[164:165], v[152:153]
	v_lshlrev_b32_e32 v150, 16, v94
	v_and_b32_e32 v151, 0xffff0000, v94
	v_lshlrev_b32_e32 v152, 16, v102
	v_and_b32_e32 v153, 0xffff0000, v102
	v_pk_add_f32 v[150:151], v[150:151], v[152:153]
	v_lshlrev_b32_e32 v152, 16, v110
	v_and_b32_e32 v153, 0xffff0000, v110
	v_pk_fma_f32 v[122:123], v[150:151], v[164:165], v[152:153]
	v_lshlrev_b32_e32 v150, 16, v95
	v_and_b32_e32 v151, 0xffff0000, v95
	v_lshlrev_b32_e32 v152, 16, v103
	v_and_b32_e32 v153, 0xffff0000, v103
	v_pk_add_f32 v[150:151], v[150:151], v[152:153]
	v_lshlrev_b32_e32 v152, 16, v111
	v_and_b32_e32 v153, 0xffff0000, v111
	v_pk_fma_f32 v[124:125], v[150:151], v[164:165], v[152:153]
	v_lshlrev_b32_e32 v150, 16, v96
	v_and_b32_e32 v151, 0xffff0000, v96
	v_lshlrev_b32_e32 v152, 16, v104
	v_and_b32_e32 v153, 0xffff0000, v104
	v_pk_add_f32 v[150:151], v[150:151], v[152:153]
	v_lshlrev_b32_e32 v152, 16, v112
	v_and_b32_e32 v153, 0xffff0000, v112
	v_pk_fma_f32 v[126:127], v[150:151], v[164:165], v[152:153]
	v_lshlrev_b32_e32 v150, 16, v97
	v_and_b32_e32 v151, 0xffff0000, v97
	v_lshlrev_b32_e32 v152, 16, v105
	v_and_b32_e32 v153, 0xffff0000, v105
	v_pk_add_f32 v[150:151], v[150:151], v[152:153]
	v_lshlrev_b32_e32 v152, 16, v113
	v_and_b32_e32 v153, 0xffff0000, v113
	v_pk_fma_f32 v[128:129], v[150:151], v[164:165], v[152:153]
	v_pk_add_f32 v[154:155], v[114:115], v[116:117]
	v_pk_add_f32 v[156:157], v[118:119], v[120:121]
	v_pk_add_f32 v[154:155], v[154:155], v[156:157]
	v_pk_add_f32 v[156:157], v[122:123], v[124:125]
	v_pk_add_f32 v[154:155], v[154:155], v[156:157]
	v_pk_add_f32 v[156:157], v[126:127], v[128:129]
	v_pk_add_f32 v[154:155], v[154:155], v[156:157]
	v_add_f32_e32 v154, v154, v155
	s_nop 1
	v_add_f32_dpp v160, v154, v154 quad_perm:[1,0,3,2] row_mask:0xf bank_mask:0xf
	s_nop 1
	v_add_f32_dpp v160, v160, v160 quad_perm:[2,3,0,1] row_mask:0xf bank_mask:0xf
	s_nop 1
	v_add_f32_dpp v160, v160, v160 row_half_mirror row_mask:0xf bank_mask:0xf
	s_nop 1
	v_add_f32_dpp v160, v160, v160 row_mirror row_mask:0xf bank_mask:0xf
	s_nop 1
	v_add_f32_dpp v160, v160, v160 row_bcast:15 row_mask:0xa bank_mask:0xf
	s_nop 1
	v_add_f32_dpp v160, v160, v160 row_bcast:31 row_mask:0xc bank_mask:0xf
	s_nop 1
	v_readlane_b32 s0, v160, 63
	s_nop 2
	v_mov_b32_e32 v170, s0
	v_mul_f32_e32 v156, 0xba800000, v170
	v_mul_f32_e32 v157, 0xba800000, v170
	v_pk_add_f32 v[114:115], v[114:115], v[156:157]
	v_pk_add_f32 v[116:117], v[116:117], v[156:157]
	v_pk_add_f32 v[118:119], v[118:119], v[156:157]
	v_pk_add_f32 v[120:121], v[120:121], v[156:157]
	v_pk_add_f32 v[122:123], v[122:123], v[156:157]
	v_pk_add_f32 v[124:125], v[124:125], v[156:157]
	v_pk_add_f32 v[126:127], v[126:127], v[156:157]
	v_pk_add_f32 v[128:129], v[128:129], v[156:157]
	v_pk_mul_f32 v[154:155], v[114:115], v[114:115]
	v_pk_fma_f32 v[154:155], v[116:117], v[116:117], v[154:155]
	v_pk_fma_f32 v[154:155], v[118:119], v[118:119], v[154:155]
	v_pk_fma_f32 v[154:155], v[120:121], v[120:121], v[154:155]
	v_pk_fma_f32 v[154:155], v[122:123], v[122:123], v[154:155]
	v_pk_fma_f32 v[154:155], v[124:125], v[124:125], v[154:155]
	v_pk_fma_f32 v[154:155], v[126:127], v[126:127], v[154:155]
	v_pk_fma_f32 v[154:155], v[128:129], v[128:129], v[154:155]
	v_add_f32_e32 v154, v154, v155
	s_nop 1
	v_add_f32_dpp v160, v154, v154 quad_perm:[1,0,3,2] row_mask:0xf bank_mask:0xf
	s_nop 1
	v_add_f32_dpp v160, v160, v160 quad_perm:[2,3,0,1] row_mask:0xf bank_mask:0xf
	s_nop 1
	v_add_f32_dpp v160, v160, v160 row_half_mirror row_mask:0xf bank_mask:0xf
	s_nop 1
	v_add_f32_dpp v160, v160, v160 row_mirror row_mask:0xf bank_mask:0xf
	s_nop 1
	v_add_f32_dpp v160, v160, v160 row_bcast:15 row_mask:0xa bank_mask:0xf
	s_nop 1
	v_add_f32_dpp v160, v160, v160 row_bcast:31 row_mask:0xc bank_mask:0xf
	s_nop 1
	v_readlane_b32 s0, v160, 63
	s_nop 2
	v_mov_b32_e32 v170, s0
	v_fmamk_f32 v154, v170, 0x3a800000, v166
	s_mov_b32 s0, 0xf800000
	v_mul_f32_e32 v155, 0x4f800000, v154
	v_cmp_gt_f32_e32 vcc, s0, v154
	s_nop 1
	v_cndmask_b32_e32 v154, v154, v155, vcc
	v_sqrt_f32_e32 v155, v154
	s_nop 0
	v_add_u32_e32 v156, -1, v155
; __device__ __forceinline__ unsigned pk2(float lo, float hi) { return pg8::cvt_pk_bf16(lo, hi); }
; __device__ __forceinline__ float bflo(unsigned u) { return __uint_as_float(u << 16); }
; __device__ __forceinline__ float bfhi(unsigned u) { return __uint_as_float(u & 0xffff0000u); }
; __device__ __forceinline__ void ln_panel(int pm, const float* resf, const bf16* rlo, const bf16* dlt, float* xo, const float* gam, const float* bet, bf16* xb, bf16* wlo, bool fin, float alpha) {
;     ...
;         for (int j = 0; j < 4; ++j) { f32x4 x; const u32x2 d = *(const u32x2*)(dlt + prow + 256 * j);
;             if (resf) x = *(const f32x4*)(resf + grow + 256 * j);
;             else { const u32x2 h = *(const u32x2*)(xb + grow + 256 * j), l = *(const u32x2*)(rlo + prow + 256 * j);
;     ...
;         const float rstd = 1.f / sqrtf(wave_sum(s2) * (1.f / DM) + LN_EPS);
; #pragma unroll
;         for (int j = 0; j < 4; ++j) { const f32x4 o = v[j] * rstd * gv[j] + bv[j];
;             if (fin) *(f32x4*)(xo + grow + 256 * j) = o;
;             else { u32x2 w; w.x = pk2(o.x, o.y); w.y = pk2(o.z, o.w); *(u32x2*)(xb + grow + 256 * j) = w;
;                    u32x2 q; q.x = pk2(o.x - bflo(w.x), o.y - bfhi(w.x)); q.y = pk2(o.z - bflo(w.y), o.w - bfhi(w.y)); *(u32x2*)(wlo + prow + 256 * j) = q; } }
	v_fma_f32 v157, -v156, v155, v154
	v_cmp_ge_f32_e64 s[0:1], 0, v157
	v_add_u32_e32 v157, 1, v155
	s_nop 0
	v_cndmask_b32_e64 v156, v155, v156, s[0:1]
	v_fma_f32 v155, -v157, v155, v154
	v_cmp_lt_f32_e64 s[0:1], 0, v155
	s_nop 1
	v_cndmask_b32_e64 v155, v156, v157, s[0:1]
	v_mul_f32_e32 v156, 0x37800000, v155
	v_cndmask_b32_e32 v155, v155, v156, vcc
	v_cmp_class_f32_e32 vcc, v154, v167
	s_nop 1
	v_cndmask_b32_e32 v154, v155, v154, vcc
	v_div_scale_f32 v155, s[0:1], v154, v154, 1.0
	v_rcp_f32_e32 v156, v155
	s_nop 0
	v_fma_f32 v157, -v155, v156, 1.0
	v_fmac_f32_e32 v156, v157, v156
	v_div_scale_f32 v157, vcc, 1.0, v154, 1.0
	v_mul_f32_e32 v158, v157, v156
	v_fma_f32 v159, -v155, v158, v157
	v_fmac_f32_e32 v158, v159, v156
	v_fma_f32 v155, -v155, v158, v157
	s_nop 0
	v_div_fmas_f32 v155, v155, v156, v158
	v_div_fixup_f32 v168, v155, v154, 1.0
	s_add_i32 s0, s98, 1
	s_lshl_b32 s0, s0, 11
	s_mov_b32 s1, 0
	v_lshl_add_u64 v[184:185], s[0:1], 0, v[172:173]
	v_lshl_add_u64 v[186:187], s[0:1], 0, v[180:181]
	v_pk_mul_f32 v[150:151], v[114:115], v[168:169] op_sel_hi:[1,0]
	v_pk_fma_f32 v[150:151], v[0:1], v[150:151], v[8:9]
	v_pk_mul_f32 v[152:153], v[116:117], v[168:169] op_sel_hi:[1,0]
	v_pk_fma_f32 v[152:153], v[2:3], v[152:153], v[10:11]
	v_cvt_pk_bf16_f32 v190, v150, v151
	v_cvt_pk_bf16_f32 v191, v152, v153
	v_lshlrev_b32_e32 v154, 16, v190
	v_and_b32_e32 v155, 0xffff0000, v190
	v_pk_add_f32 v[150:151], v[150:151], v[154:155] neg_lo:[0,1] neg_hi:[0,1]
	v_cvt_pk_bf16_f32 v198, v150, v151
	v_lshlrev_b32_e32 v154, 16, v191
	v_and_b32_e32 v155, 0xffff0000, v191
	v_pk_add_f32 v[152:153], v[152:153], v[154:155] neg_lo:[0,1] neg_hi:[0,1]
	v_cvt_pk_bf16_f32 v199, v152, v153
	v_pk_mul_f32 v[150:151], v[118:119], v[168:169] op_sel_hi:[1,0]
	v_pk_fma_f32 v[150:151], v[4:5], v[150:151], v[12:13]
	v_pk_mul_f32 v[152:153], v[120:121], v[168:169] op_sel_hi:[1,0]
	v_pk_fma_f32 v[152:153], v[6:7], v[152:153], v[14:15]
	v_cvt_pk_bf16_f32 v192, v150, v151
	v_cvt_pk_bf16_f32 v193, v152, v153
	v_lshlrev_b32_e32 v154, 16, v192
	v_and_b32_e32 v155, 0xffff0000, v192
	v_pk_add_f32 v[150:151], v[150:151], v[154:155] neg_lo:[0,1] neg_hi:[0,1]
	v_cvt_pk_bf16_f32 v200, v150, v151
	v_lshlrev_b32_e32 v154, 16, v193
	v_and_b32_e32 v155, 0xffff0000, v193
	v_pk_add_f32 v[152:153], v[152:153], v[154:155] neg_lo:[0,1] neg_hi:[0,1]
	v_cvt_pk_bf16_f32 v201, v152, v153
	v_pk_mul_f32 v[150:151], v[122:123], v[168:169] op_sel_hi:[1,0]
	v_pk_fma_f32 v[150:151], v[16:17], v[150:151], v[24:25]
	v_pk_mul_f32 v[152:153], v[124:125], v[168:169] op_sel_hi:[1,0]
	v_pk_fma_f32 v[152:153], v[18:19], v[152:153], v[26:27]
	v_cvt_pk_bf16_f32 v194, v150, v151
	v_cvt_pk_bf16_f32 v195, v152, v153
	v_lshlrev_b32_e32 v154, 16, v194
	v_and_b32_e32 v155, 0xffff0000, v194
	v_pk_add_f32 v[150:151], v[150:151], v[154:155] neg_lo:[0,1] neg_hi:[0,1]
	v_cvt_pk_bf16_f32 v202, v150, v151
	v_lshlrev_b32_e32 v154, 16, v195
	v_and_b32_e32 v155, 0xffff0000, v195
	v_pk_add_f32 v[152:153], v[152:153], v[154:155] neg_lo:[0,1] neg_hi:[0,1]
	v_cvt_pk_bf16_f32 v203, v152, v153
	v_pk_mul_f32 v[150:151], v[126:127], v[168:169] op_sel_hi:[1,0]
	v_pk_fma_f32 v[150:151], v[20:21], v[150:151], v[28:29]
	v_pk_mul_f32 v[152:153], v[128:129], v[168:169] op_sel_hi:[1,0]
	v_pk_fma_f32 v[152:153], v[22:23], v[152:153], v[30:31]
	v_cvt_pk_bf16_f32 v196, v150, v151
	v_cvt_pk_bf16_f32 v197, v152, v153
	v_lshlrev_b32_e32 v154, 16, v196
	v_and_b32_e32 v155, 0xffff0000, v196
	v_pk_add_f32 v[150:151], v[150:151], v[154:155] neg_lo:[0,1] neg_hi:[0,1]
	v_cvt_pk_bf16_f32 v204, v150, v151
	v_lshlrev_b32_e32 v154, 16, v197
	v_and_b32_e32 v155, 0xffff0000, v197
	v_pk_add_f32 v[152:153], v[152:153], v[154:155] neg_lo:[0,1] neg_hi:[0,1]
	v_cvt_pk_bf16_f32 v205, v152, v153
	global_store_dwordx2 v[184:185], v[190:191], off offset:-1024
	global_store_dwordx2 v[184:185], v[192:193], off offset:-512
	global_store_dwordx2 v[184:185], v[194:195], off offset:0
	global_store_dwordx2 v[184:185], v[196:197], off offset:512
	global_store_dwordx2 v[186:187], v[198:199], off offset:0
	global_store_dwordx2 v[186:187], v[200:201], off offset:512
	global_store_dwordx2 v[186:187], v[202:203], off offset:1024
	global_store_dwordx2 v[186:187], v[204:205], off offset:1536
	s_add_i32 s0, s98, 3
	s_min_u32 s0, s0, 31
	s_lshl_b32 s0, s0, 11
	s_mov_b32 s1, 0
	v_lshl_add_u64 v[184:185], s[0:1], 0, v[178:179]
	v_lshl_add_u64 v[186:187], s[0:1], 0, v[172:173]
	v_lshl_add_u64 v[188:189], s[0:1], 0, v[176:177]
	global_load_dwordx2 v[106:107], v[184:185], off offset:-1024 nt
	global_load_dwordx2 v[108:109], v[184:185], off offset:-512 nt
	global_load_dwordx2 v[110:111], v[184:185], off offset:0 nt
	global_load_dwordx2 v[112:113], v[184:185], off offset:512 nt
	global_load_dwordx2 v[90:91], v[186:187], off offset:-1024
	global_load_dwordx2 v[92:93], v[186:187], off offset:-512
	global_load_dwordx2 v[94:95], v[186:187], off offset:0
	global_load_dwordx2 v[96:97], v[186:187], off offset:512
	global_load_dwordx2 v[98:99], v[188:189], off offset:-1024 nt
	global_load_dwordx2 v[100:101], v[188:189], off offset:-512 nt
	global_load_dwordx2 v[102:103], v[188:189], off offset:0 nt
	global_load_dwordx2 v[104:105], v[188:189], off offset:512 nt
	s_add_i32 s98, s98, 2
	s_cmp_lt_u32 s98, 32
	s_cbranch_scc1 .Lmy_ln2h_loop
	s_waitcnt vmcnt(0)
	s_branch .LBB0_467

; __device__ __forceinline__ float bflo(unsigned u) { return __uint_as_float(u << 16); }
; __device__ __forceinline__ float bfhi(unsigned u) { return __uint_as_float(u & 0xffff0000u); }
; __device__ __forceinline__ void ln_panel(int pm, const float* resf, const bf16* rlo, const bf16* dlt, float* xo, const float* gam, const float* bet, bf16* xb, bf16* wlo, bool fin, float alpha) {
;     ...
;         for (int j = 0; j < 4; ++j) { f32x4 x; const u32x2 d = *(const u32x2*)(dlt + prow + 256 * j);
;             if (resf) x = *(const f32x4*)(resf + grow + 256 * j);
;             else { const u32x2 h = *(const u32x2*)(xb + grow + 256 * j), l = *(const u32x2*)(rlo + prow + 256 * j);
;                    x = (f32x4){bflo(h.x) + bflo(l.x), bfhi(h.x) + bfhi(l.x), bflo(h.y) + bflo(l.y), bfhi(h.y) + bfhi(l.y)}; }
;             v[j] = (f32x4){x.x * alpha + bflo(d.x), x.y * alpha + bfhi(d.x), x.z * alpha + bflo(d.y), x.w * alpha + bfhi(d.y)}; s += (v[j].x + v[j].y) + (v[j].z + v[j].w); }
;         const float mean = wave_sum(s) * (1.f / DM); float s2 = 0.f;
; #pragma unroll
;         for (int j = 0; j < 4; ++j) { v[j] = v[j] - mean; s2 += (v[j].x * v[j].x + v[j].y * v[j].y) + (v[j].z * v[j].z + v[j].w * v[j].w); }
;         const float rstd = 1.f / sqrtf(wave_sum(s2) * (1.f / DM) + LN_EPS);
.Lmy_ln2f_entry:
	v_lshlrev_b32_e32 v150, 16, v66
	v_and_b32_e32 v151, 0xffff0000, v66
	v_lshlrev_b32_e32 v152, 16, v74
	v_and_b32_e32 v153, 0xffff0000, v74
	v_pk_add_f32 v[150:151], v[150:151], v[152:153]
	v_lshlrev_b32_e32 v152, 16, v82
	v_and_b32_e32 v153, 0xffff0000, v82
	v_pk_fma_f32 v[114:115], v[150:151], v[164:165], v[152:153]
	v_lshlrev_b32_e32 v150, 16, v67
	v_and_b32_e32 v151, 0xffff0000, v67
	v_lshlrev_b32_e32 v152, 16, v75
	v_and_b32_e32 v153, 0xffff0000, v75
	v_pk_add_f32 v[150:151], v[150:151], v[152:153]
	v_lshlrev_b32_e32 v152, 16, v83
	v_and_b32_e32 v153, 0xffff0000, v83
	v_pk_fma_f32 v[116:117], v[150:151], v[164:165], v[152:153]
	v_lshlrev_b32_e32 v150, 16, v68
	v_and_b32_e32 v151, 0xffff0000, v68
	v_lshlrev_b32_e32 v152, 16, v76
	v_and_b32_e32 v153, 0xffff0000, v76
	v_pk_add_f32 v[150:151], v[150:151], v[152:153]
	v_lshlrev_b32_e32 v152, 16, v84
	v_and_b32_e32 v153, 0xffff0000, v84
	v_pk_fma_f32 v[118:119], v[150:151], v[164:165], v[152:153]
	v_lshlrev_b32_e32 v150, 16, v69
	v_and_b32_e32 v151, 0xffff0000, v69
	v_lshlrev_b32_e32 v152, 16, v77
	v_and_b32_e32 v153, 0xffff0000, v77
	v_pk_add_f32 v[150:151], v[150:151], v[152:153]
	v_lshlrev_b32_e32 v152, 16, v85
	v_and_b32_e32 v153, 0xffff0000, v85
	v_pk_fma_f32 v[120:121], v[150:151], v[164:165], v[152:153]
	v_lshlrev_b32_e32 v150, 16, v70
	v_and_b32_e32 v151, 0xffff0000, v70
	v_lshlrev_b32_e32 v152, 16, v78
	v_and_b32_e32 v153, 0xffff0000, v78
	v_pk_add_f32 v[150:151], v[150:151], v[152:153]
	v_lshlrev_b32_e32 v152, 16, v86
	v_and_b32_e32 v153, 0xffff0000, v86
	v_pk_fma_f32 v[122:123], v[150:151], v[164:165], v[152:153]
	v_lshlrev_b32_e32 v150, 16, v71
	v_and_b32_e32 v151, 0xffff0000, v71
	v_lshlrev_b32_e32 v152, 16, v79
	v_and_b32_e32 v153, 0xffff0000, v79
	v_pk_add_f32 v[150:151], v[150:151], v[152:153]
	v_lshlrev_b32_e32 v152, 16, v87
	v_and_b32_e32 v153, 0xffff0000, v87
	v_pk_fma_f32 v[124:125], v[150:151], v[164:165], v[152:153]
	v_lshlrev_b32_e32 v150, 16, v72
	v_and_b32_e32 v151, 0xffff0000, v72
	v_lshlrev_b32_e32 v152, 16, v80
	v_and_b32_e32 v153, 0xffff0000, v80
	v_pk_add_f32 v[150:151], v[150:151], v[152:153]
	v_lshlrev_b32_e32 v152, 16, v88
	v_and_b32_e32 v153, 0xffff0000, v88
	v_pk_fma_f32 v[126:127], v[150:151], v[164:165], v[152:153]
	v_lshlrev_b32_e32 v150, 16, v73
	v_and_b32_e32 v151, 0xffff0000, v73
	v_lshlrev_b32_e32 v152, 16, v81
	v_and_b32_e32 v153, 0xffff0000, v81
	v_pk_add_f32 v[150:151], v[150:151], v[152:153]
	v_lshlrev_b32_e32 v152, 16, v89
	v_and_b32_e32 v153, 0xffff0000, v89
	v_pk_fma_f32 v[128:129], v[150:151], v[164:165], v[152:153]
	v_pk_add_f32 v[154:155], v[114:115], v[116:117]
	v_pk_add_f32 v[156:157], v[118:119], v[120:121]
	v_pk_add_f32 v[154:155], v[154:155], v[156:157]
	v_pk_add_f32 v[156:157], v[122:123], v[124:125]
	v_pk_add_f32 v[154:155], v[154:155], v[156:157]
	v_pk_add_f32 v[156:157], v[126:127], v[128:129]
	v_pk_add_f32 v[154:155], v[154:155], v[156:157]
	v_add_f32_e32 v154, v154, v155
	s_nop 1
	v_add_f32_dpp v160, v154, v154 quad_perm:[1,0,3,2] row_mask:0xf bank_mask:0xf
	s_nop 1
	v_add_f32_dpp v160, v160, v160 quad_perm:[2,3,0,1] row_mask:0xf bank_mask:0xf
	s_nop 1
	v_add_f32_dpp v160, v160, v160 row_half_mirror row_mask:0xf bank_mask:0xf
	s_nop 1
	v_add_f32_dpp v160, v160, v160 row_mirror row_mask:0xf bank_mask:0xf
	s_nop 1
	v_add_f32_dpp v160, v160, v160 row_bcast:15 row_mask:0xa bank_mask:0xf
	s_nop 1
	v_add_f32_dpp v160, v160, v160 row_bcast:31 row_mask:0xc bank_mask:0xf
	s_nop 1
	v_readlane_b32 s0, v160, 63
	s_nop 2
	v_mov_b32_e32 v170, s0
	v_mul_f32_e32 v156, 0xba800000, v170
	v_mul_f32_e32 v157, 0xba800000, v170
	v_pk_add_f32 v[114:115], v[114:115], v[156:157]
	v_pk_add_f32 v[116:117], v[116:117], v[156:157]
	v_pk_add_f32 v[118:119], v[118:119], v[156:157]
	v_pk_add_f32 v[120:121], v[120:121], v[156:157]
	v_pk_add_f32 v[122:123], v[122:123], v[156:157]
	v_pk_add_f32 v[124:125], v[124:125], v[156:157]
	v_pk_add_f32 v[126:127], v[126:127], v[156:157]
	v_pk_add_f32 v[128:129], v[128:129], v[156:157]
	v_pk_mul_f32 v[154:155], v[114:115], v[114:115]
	v_pk_fma_f32 v[154:155], v[116:117], v[116:117], v[154:155]
	v_pk_fma_f32 v[154:155], v[118:119], v[118:119], v[154:155]
	v_pk_fma_f32 v[154:155], v[120:121], v[120:121], v[154:155]
	v_pk_fma_f32 v[154:155], v[122:123], v[122:123], v[154:155]
	v_pk_fma_f32 v[154:155], v[124:125], v[124:125], v[154:155]
	v_pk_fma_f32 v[154:155], v[126:127], v[126:127], v[154:155]
	v_pk_fma_f32 v[154:155], v[128:129], v[128:129], v[154:155]
	v_add_f32_e32 v154, v154, v155
	s_nop 1
	v_add_f32_dpp v160, v154, v154 quad_perm:[1,0,3,2] row_mask:0xf bank_mask:0xf
	s_nop 1
	v_add_f32_dpp v160, v160, v160 quad_perm:[2,3,0,1] row_mask:0xf bank_mask:0xf
	s_nop 1
	v_add_f32_dpp v160, v160, v160 row_half_mirror row_mask:0xf bank_mask:0xf
	s_nop 1
	v_add_f32_dpp v160, v160, v160 row_mirror row_mask:0xf bank_mask:0xf
	s_nop 1
	v_add_f32_dpp v160, v160, v160 row_bcast:15 row_mask:0xa bank_mask:0xf
	s_nop 1
	v_add_f32_dpp v160, v160, v160 row_bcast:31 row_mask:0xc bank_mask:0xf
	s_nop 1
	v_readlane_b32 s0, v160, 63
	s_nop 2
	v_mov_b32_e32 v170, s0
	v_fmamk_f32 v154, v170, 0x3a800000, v166
	s_mov_b32 s0, 0xf800000
	v_mul_f32_e32 v155, 0x4f800000, v154
	v_cmp_gt_f32_e32 vcc, s0, v154
	s_nop 1
	v_cndmask_b32_e32 v154, v154, v155, vcc
	v_sqrt_f32_e32 v155, v154
	s_nop 0
	v_add_u32_e32 v156, -1, v155
	v_fma_f32 v157, -v156, v155, v154
	v_cmp_ge_f32_e64 s[0:1], 0, v157
	v_add_u32_e32 v157, 1, v155
	s_nop 0
	v_cndmask_b32_e64 v156, v155, v156, s[0:1]
	v_fma_f32 v155, -v157, v155, v154
	v_cmp_lt_f32_e64 s[0:1], 0, v155
	s_nop 1
	v_cndmask_b32_e64 v155, v156, v157, s[0:1]
	v_mul_f32_e32 v156, 0x37800000, v155
; __device__ __forceinline__ float bflo(unsigned u) { return __uint_as_float(u << 16); }
; __device__ __forceinline__ float bfhi(unsigned u) { return __uint_as_float(u & 0xffff0000u); }
; __device__ __forceinline__ void ln_panel(int pm, const float* resf, const bf16* rlo, const bf16* dlt, float* xo, const float* gam, const float* bet, bf16* xb, bf16* wlo, bool fin, float alpha) {
;     ...
;         for (int j = 0; j < 4; ++j) { f32x4 x; const u32x2 d = *(const u32x2*)(dlt + prow + 256 * j);
;             if (resf) x = *(const f32x4*)(resf + grow + 256 * j);
;             else { const u32x2 h = *(const u32x2*)(xb + grow + 256 * j), l = *(const u32x2*)(rlo + prow + 256 * j);
;                    x = (f32x4){bflo(h.x) + bflo(l.x), bfhi(h.x) + bfhi(l.x), bflo(h.y) + bflo(l.y), bfhi(h.y) + bfhi(l.y)}; }
;             v[j] = (f32x4){x.x * alpha + bflo(d.x), x.y * alpha + bfhi(d.x), x.z * alpha + bflo(d.y), x.w * alpha + bfhi(d.y)}; s += (v[j].x + v[j].y) + (v[j].z + v[j].w); }
;     ...
;         const float rstd = 1.f / sqrtf(wave_sum(s2) * (1.f / DM) + LN_EPS);
; #pragma unroll
;         for (int j = 0; j < 4; ++j) { const f32x4 o = v[j] * rstd * gv[j] + bv[j];
;             if (fin) *(f32x4*)(xo + grow + 256 * j) = o;
	v_cndmask_b32_e32 v155, v155, v156, vcc
	v_cmp_class_f32_e32 vcc, v154, v167
	s_nop 1
	v_cndmask_b32_e32 v154, v155, v154, vcc
	v_div_scale_f32 v155, s[0:1], v154, v154, 1.0
	v_rcp_f32_e32 v156, v155
	s_nop 0
	v_fma_f32 v157, -v155, v156, 1.0
	v_fmac_f32_e32 v156, v157, v156
	v_div_scale_f32 v157, vcc, 1.0, v154, 1.0
	v_mul_f32_e32 v158, v157, v156
	v_fma_f32 v159, -v155, v158, v157
	v_fmac_f32_e32 v158, v159, v156
	v_fma_f32 v155, -v155, v158, v157
	s_nop 0
	v_div_fmas_f32 v155, v155, v156, v158
	v_div_fixup_f32 v168, v155, v154, 1.0
	s_add_i32 s0, s98, 0
	s_lshl_b32 s0, s0, 11
	s_mov_b32 s1, 0
	v_lshl_add_u64 v[184:185], s[0:1], 1, v[182:183]
	v_pk_mul_f32 v[190:191], v[114:115], v[168:169] op_sel_hi:[1,0]
	v_pk_fma_f32 v[190:191], v[0:1], v[190:191], v[8:9]
	v_pk_mul_f32 v[192:193], v[116:117], v[168:169] op_sel_hi:[1,0]
	v_pk_fma_f32 v[192:193], v[2:3], v[192:193], v[10:11]
	v_pk_mul_f32 v[194:195], v[118:119], v[168:169] op_sel_hi:[1,0]
	v_pk_fma_f32 v[194:195], v[4:5], v[194:195], v[12:13]
	v_pk_mul_f32 v[196:197], v[120:121], v[168:169] op_sel_hi:[1,0]
	v_pk_fma_f32 v[196:197], v[6:7], v[196:197], v[14:15]
	v_pk_mul_f32 v[198:199], v[122:123], v[168:169] op_sel_hi:[1,0]
	v_pk_fma_f32 v[198:199], v[16:17], v[198:199], v[24:25]
	v_pk_mul_f32 v[200:201], v[124:125], v[168:169] op_sel_hi:[1,0]
	v_pk_fma_f32 v[200:201], v[18:19], v[200:201], v[26:27]
	v_pk_mul_f32 v[202:203], v[126:127], v[168:169] op_sel_hi:[1,0]
	v_pk_fma_f32 v[202:203], v[20:21], v[202:203], v[28:29]
	v_pk_mul_f32 v[204:205], v[128:129], v[168:169] op_sel_hi:[1,0]
	v_pk_fma_f32 v[204:205], v[22:23], v[204:205], v[30:31]
	global_store_dwordx4 v[184:185], v[190:193], off offset:-2048
	global_store_dwordx4 v[184:185], v[194:197], off offset:-1024
	global_store_dwordx4 v[184:185], v[198:201], off offset:0
	global_store_dwordx4 v[184:185], v[202:205], off offset:1024
	s_add_i32 s0, s98, 2
	s_min_u32 s0, s0, 31
	s_lshl_b32 s0, s0, 11
	s_mov_b32 s1, 0
	v_lshl_add_u64 v[184:185], s[0:1], 0, v[178:179]
	v_lshl_add_u64 v[186:187], s[0:1], 0, v[172:173]
	v_lshl_add_u64 v[188:189], s[0:1], 0, v[176:177]
	global_load_dwordx2 v[82:83], v[184:185], off offset:-1024 nt
	global_load_dwordx2 v[84:85], v[184:185], off offset:-512 nt
	global_load_dwordx2 v[86:87], v[184:185], off offset:0 nt
	global_load_dwordx2 v[88:89], v[184:185], off offset:512 nt
	global_load_dwordx2 v[66:67], v[186:187], off offset:-1024
	global_load_dwordx2 v[68:69], v[186:187], off offset:-512
	global_load_dwordx2 v[70:71], v[186:187], off offset:0
	global_load_dwordx2 v[72:73], v[186:187], off offset:512
	global_load_dwordx2 v[74:75], v[188:189], off offset:-1024 nt
	global_load_dwordx2 v[76:77], v[188:189], off offset:-512 nt
	global_load_dwordx2 v[78:79], v[188:189], off offset:0 nt
	global_load_dwordx2 v[80:81], v[188:189], off offset:512 nt
	s_waitcnt vmcnt(16)
	v_lshlrev_b32_e32 v150, 16, v90
	v_and_b32_e32 v151, 0xffff0000, v90
	v_lshlrev_b32_e32 v152, 16, v98
	v_and_b32_e32 v153, 0xffff0000, v98
	v_pk_add_f32 v[150:151], v[150:151], v[152:153]
	v_lshlrev_b32_e32 v152, 16, v106
	v_and_b32_e32 v153, 0xffff0000, v106
	v_pk_fma_f32 v[114:115], v[150:151], v[164:165], v[152:153]
	v_lshlrev_b32_e32 v150, 16, v91
	v_and_b32_e32 v151, 0xffff0000, v91
	v_lshlrev_b32_e32 v152, 16, v99
	v_and_b32_e32 v153, 0xffff0000, v99
	v_pk_add_f32 v[150:151], v[150:151], v[152:153]
	v_lshlrev_b32_e32 v152, 16, v107
	v_and_b32_e32 v153, 0xffff0000, v107
	v_pk_fma_f32 v[116:117], v[150:151], v[164:165], v[152:153]
	v_lshlrev_b32_e32 v150, 16, v92
	v_and_b32_e32 v151, 0xffff0000, v92
	v_lshlrev_b32_e32 v152, 16, v100
	v_and_b32_e32 v153, 0xffff0000, v100
	v_pk_add_f32 v[150:151], v[150:151], v[152:153]
	v_lshlrev_b32_e32 v152, 16, v108
	v_and_b32_e32 v153, 0xffff0000, v108
	v_pk_fma_f32 v[118:119], v[150:151], v[164:165], v[152:153]
	v_lshlrev_b32_e32 v150, 16, v93
	v_and_b32_e32 v151, 0xffff0000, v93
	v_lshlrev_b32_e32 v152, 16, v101
	v_and_b32_e32 v153, 0xffff0000, v101
	v_pk_add_f32 v[150:151], v[150:151], v[152:153]
	v_lshlrev_b32_e32 v152, 16, v109
	v_and_b32_e32 v153, 0xffff0000, v109
	v_pk_fma_f32 v[120:121], v[150:151], v[164:165], v[152:153]
	v_lshlrev_b32_e32 v150, 16, v94
	v_and_b32_e32 v151, 0xffff0000, v94
	v_lshlrev_b32_e32 v152, 16, v102
	v_and_b32_e32 v153, 0xffff0000, v102
	v_pk_add_f32 v[150:151], v[150:151], v[152:153]
	v_lshlrev_b32_e32 v152, 16, v110
	v_and_b32_e32 v153, 0xffff0000, v110
	v_pk_fma_f32 v[122:123], v[150:151], v[164:165], v[152:153]
	v_lshlrev_b32_e32 v150, 16, v95
	v_and_b32_e32 v151, 0xffff0000, v95
	v_lshlrev_b32_e32 v152, 16, v103
	v_and_b32_e32 v153, 0xffff0000, v103
	v_pk_add_f32 v[150:151], v[150:151], v[152:153]
	v_lshlrev_b32_e32 v152, 16, v111
	v_and_b32_e32 v153, 0xffff0000, v111
	v_pk_fma_f32 v[124:125], v[150:151], v[164:165], v[152:153]
	v_lshlrev_b32_e32 v150, 16, v96
	v_and_b32_e32 v151, 0xffff0000, v96
	v_lshlrev_b32_e32 v152, 16, v104
	v_and_b32_e32 v153, 0xffff0000, v104
	v_pk_add_f32 v[150:151], v[150:151], v[152:153]
	v_lshlrev_b32_e32 v152, 16, v112
	v_and_b32_e32 v153, 0xffff0000, v112
	v_pk_fma_f32 v[126:127], v[150:151], v[164:165], v[152:153]
	v_lshlrev_b32_e32 v150, 16, v97
	v_and_b32_e32 v151, 0xffff0000, v97
	v_lshlrev_b32_e32 v152, 16, v105
	v_and_b32_e32 v153, 0xffff0000, v105
	v_pk_add_f32 v[150:151], v[150:151], v[152:153]
	v_lshlrev_b32_e32 v152, 16, v113
	v_and_b32_e32 v153, 0xffff0000, v113
	v_pk_fma_f32 v[128:129], v[150:151], v[164:165], v[152:153]
	v_pk_add_f32 v[154:155], v[114:115], v[116:117]
	v_pk_add_f32 v[156:157], v[118:119], v[120:121]
	v_pk_add_f32 v[154:155], v[154:155], v[156:157]
	v_pk_add_f32 v[156:157], v[122:123], v[124:125]
; __device__ __forceinline__ void ln_panel(int pm, const float* resf, const bf16* rlo, const bf16* dlt, float* xo, const float* gam, const float* bet, bf16* xb, bf16* wlo, bool fin, float alpha) {
;     ...
;         for (int j = 0; j < 4; ++j) { f32x4 x; const u32x2 d = *(const u32x2*)(dlt + prow + 256 * j);
;             if (resf) x = *(const f32x4*)(resf + grow + 256 * j);
;     ...
;         const float mean = wave_sum(s) * (1.f / DM); float s2 = 0.f;
; #pragma unroll
;         for (int j = 0; j < 4; ++j) { v[j] = v[j] - mean; s2 += (v[j].x * v[j].x + v[j].y * v[j].y) + (v[j].z * v[j].z + v[j].w * v[j].w); }
;         const float rstd = 1.f / sqrtf(wave_sum(s2) * (1.f / DM) + LN_EPS);
; #pragma unroll
;         for (int j = 0; j < 4; ++j) { const f32x4 o = v[j] * rstd * gv[j] + bv[j];
;             if (fin) *(f32x4*)(xo + grow + 256 * j) = o;
	v_pk_add_f32 v[154:155], v[154:155], v[156:157]
	v_pk_add_f32 v[156:157], v[126:127], v[128:129]
	v_pk_add_f32 v[154:155], v[154:155], v[156:157]
	v_add_f32_e32 v154, v154, v155
	s_nop 1
	v_add_f32_dpp v160, v154, v154 quad_perm:[1,0,3,2] row_mask:0xf bank_mask:0xf
	s_nop 1
	v_add_f32_dpp v160, v160, v160 quad_perm:[2,3,0,1] row_mask:0xf bank_mask:0xf
	s_nop 1
	v_add_f32_dpp v160, v160, v160 row_half_mirror row_mask:0xf bank_mask:0xf
	s_nop 1
	v_add_f32_dpp v160, v160, v160 row_mirror row_mask:0xf bank_mask:0xf
	s_nop 1
	v_add_f32_dpp v160, v160, v160 row_bcast:15 row_mask:0xa bank_mask:0xf
	s_nop 1
	v_add_f32_dpp v160, v160, v160 row_bcast:31 row_mask:0xc bank_mask:0xf
	s_nop 1
	v_readlane_b32 s0, v160, 63
	s_nop 2
	v_mov_b32_e32 v170, s0
	v_mul_f32_e32 v156, 0xba800000, v170
	v_mul_f32_e32 v157, 0xba800000, v170
	v_pk_add_f32 v[114:115], v[114:115], v[156:157]
	v_pk_add_f32 v[116:117], v[116:117], v[156:157]
	v_pk_add_f32 v[118:119], v[118:119], v[156:157]
	v_pk_add_f32 v[120:121], v[120:121], v[156:157]
	v_pk_add_f32 v[122:123], v[122:123], v[156:157]
	v_pk_add_f32 v[124:125], v[124:125], v[156:157]
	v_pk_add_f32 v[126:127], v[126:127], v[156:157]
	v_pk_add_f32 v[128:129], v[128:129], v[156:157]
	v_pk_mul_f32 v[154:155], v[114:115], v[114:115]
	v_pk_fma_f32 v[154:155], v[116:117], v[116:117], v[154:155]
	v_pk_fma_f32 v[154:155], v[118:119], v[118:119], v[154:155]
	v_pk_fma_f32 v[154:155], v[120:121], v[120:121], v[154:155]
	v_pk_fma_f32 v[154:155], v[122:123], v[122:123], v[154:155]
	v_pk_fma_f32 v[154:155], v[124:125], v[124:125], v[154:155]
	v_pk_fma_f32 v[154:155], v[126:127], v[126:127], v[154:155]
	v_pk_fma_f32 v[154:155], v[128:129], v[128:129], v[154:155]
	v_add_f32_e32 v154, v154, v155
	s_nop 1
	v_add_f32_dpp v160, v154, v154 quad_perm:[1,0,3,2] row_mask:0xf bank_mask:0xf
	s_nop 1
	v_add_f32_dpp v160, v160, v160 quad_perm:[2,3,0,1] row_mask:0xf bank_mask:0xf
	s_nop 1
	v_add_f32_dpp v160, v160, v160 row_half_mirror row_mask:0xf bank_mask:0xf
	s_nop 1
	v_add_f32_dpp v160, v160, v160 row_mirror row_mask:0xf bank_mask:0xf
	s_nop 1
	v_add_f32_dpp v160, v160, v160 row_bcast:15 row_mask:0xa bank_mask:0xf
	s_nop 1
	v_add_f32_dpp v160, v160, v160 row_bcast:31 row_mask:0xc bank_mask:0xf
	s_nop 1
	v_readlane_b32 s0, v160, 63
	s_nop 2
	v_mov_b32_e32 v170, s0
	v_fmamk_f32 v154, v170, 0x3a800000, v166
	s_mov_b32 s0, 0xf800000
	v_mul_f32_e32 v155, 0x4f800000, v154
	v_cmp_gt_f32_e32 vcc, s0, v154
	s_nop 1
	v_cndmask_b32_e32 v154, v154, v155, vcc
	v_sqrt_f32_e32 v155, v154
	s_nop 0
	v_add_u32_e32 v156, -1, v155
	v_fma_f32 v157, -v156, v155, v154
	v_cmp_ge_f32_e64 s[0:1], 0, v157
	v_add_u32_e32 v157, 1, v155
	s_nop 0
	v_cndmask_b32_e64 v156, v155, v156, s[0:1]
	v_fma_f32 v155, -v157, v155, v154
	v_cmp_lt_f32_e64 s[0:1], 0, v155
	s_nop 1
	v_cndmask_b32_e64 v155, v156, v157, s[0:1]
	v_mul_f32_e32 v156, 0x37800000, v155
	v_cndmask_b32_e32 v155, v155, v156, vcc
	v_cmp_class_f32_e32 vcc, v154, v167
	s_nop 1
	v_cndmask_b32_e32 v154, v155, v154, vcc
	v_div_scale_f32 v155, s[0:1], v154, v154, 1.0
	v_rcp_f32_e32 v156, v155
	s_nop 0
	v_fma_f32 v157, -v155, v156, 1.0
	v_fmac_f32_e32 v156, v157, v156
	v_div_scale_f32 v157, vcc, 1.0, v154, 1.0
	v_mul_f32_e32 v158, v157, v156
	v_fma_f32 v159, -v155, v158, v157
	v_fmac_f32_e32 v158, v159, v156
	v_fma_f32 v155, -v155, v158, v157
	s_nop 0
	v_div_fmas_f32 v155, v155, v156, v158
	v_div_fixup_f32 v168, v155, v154, 1.0
	s_add_i32 s0, s98, 1
	s_lshl_b32 s0, s0, 11
	s_mov_b32 s1, 0
	v_lshl_add_u64 v[184:185], s[0:1], 1, v[182:183]
	v_pk_mul_f32 v[190:191], v[114:115], v[168:169] op_sel_hi:[1,0]
	v_pk_fma_f32 v[190:191], v[0:1], v[190:191], v[8:9]
	v_pk_mul_f32 v[192:193], v[116:117], v[168:169] op_sel_hi:[1,0]
	v_pk_fma_f32 v[192:193], v[2:3], v[192:193], v[10:11]
	v_pk_mul_f32 v[194:195], v[118:119], v[168:169] op_sel_hi:[1,0]
	v_pk_fma_f32 v[194:195], v[4:5], v[194:195], v[12:13]
	v_pk_mul_f32 v[196:197], v[120:121], v[168:169] op_sel_hi:[1,0]
	v_pk_fma_f32 v[196:197], v[6:7], v[196:197], v[14:15]
	v_pk_mul_f32 v[198:199], v[122:123], v[168:169] op_sel_hi:[1,0]
	v_pk_fma_f32 v[198:199], v[16:17], v[198:199], v[24:25]
	v_pk_mul_f32 v[200:201], v[124:125], v[168:169] op_sel_hi:[1,0]
	v_pk_fma_f32 v[200:201], v[18:19], v[200:201], v[26:27]
	v_pk_mul_f32 v[202:203], v[126:127], v[168:169] op_sel_hi:[1,0]
	v_pk_fma_f32 v[202:203], v[20:21], v[202:203], v[28:29]
	v_pk_mul_f32 v[204:205], v[128:129], v[168:169] op_sel_hi:[1,0]
	v_pk_fma_f32 v[204:205], v[22:23], v[204:205], v[30:31]
	global_store_dwordx4 v[184:185], v[190:193], off offset:-2048
	global_store_dwordx4 v[184:185], v[194:197], off offset:-1024
	global_store_dwordx4 v[184:185], v[198:201], off offset:0
	global_store_dwordx4 v[184:185], v[202:205], off offset:1024
	s_add_i32 s0, s98, 3
	s_min_u32 s0, s0, 31
	s_lshl_b32 s0, s0, 11
	s_mov_b32 s1, 0
	v_lshl_add_u64 v[184:185], s[0:1], 0, v[178:179]
	v_lshl_add_u64 v[186:187], s[0:1], 0, v[172:173]
	v_lshl_add_u64 v[188:189], s[0:1], 0, v[176:177]
	global_load_dwordx2 v[106:107], v[184:185], off offset:-1024 nt
	global_load_dwordx2 v[108:109], v[184:185], off offset:-512 nt
	global_load_dwordx2 v[110:111], v[184:185], off offset:0 nt
	global_load_dwordx2 v[112:113], v[184:185], off offset:512 nt
	global_load_dwordx2 v[90:91], v[186:187], off offset:-1024
	global_load_dwordx2 v[92:93], v[186:187], off offset:-512
	global_load_dwordx2 v[94:95], v[186:187], off offset:0
	global_load_dwordx2 v[96:97], v[186:187], off offset:512
	global_load_dwordx2 v[98:99], v[188:189], off offset:-1024 nt
	global_load_dwordx2 v[100:101], v[188:189], off offset:-512 nt
	global_load_dwordx2 v[102:103], v[188:189], off offset:0 nt
	global_load_dwordx2 v[104:105], v[188:189], off offset:512 nt
	s_add_i32 s98, s98, 2
	s_cmp_lt_u32 s98, 32
	s_cbranch_scc1 .Lmy_ln2f_loop
	s_waitcnt vmcnt(0)
	s_branch .LBB0_467
